# base12 + A22: DeltaNet WY forward-substitution coefficient ds_read_b128 software-pipelined into a ring of dead quads, counted lgkmcnt waits
# speedup vs baseline: 1.0105x; 1.0105x over previous
; #define LAS __attribute__((address_space(3)))
; __device__ __forceinline__ void solve_diag(float (&x)[64], const LAS float* AT, const int o, const int ja, const int jb) {
; #pragma unroll
;     for (int j = ja; j < jb; ++j) { const float xj = x[o + j];
;         int z = 0; if (j >= 2) asm("" : "+v"(z) : "v"(x[o + j - 2]));
;         const LAS float* ATj = AT + z;
; #pragma unroll
;         for (int i4 = ((j + 1) >> 2) << 2; i4 < 32; i4 += 4) { const f32x4 av = *(const LAS f32x4*)(ATj + j * 36 + i4);
; #pragma unroll
;             for (int t = 0; t < 4; ++t) if (i4 + t > j) x[o + i4 + t] -= av[t] * xj; } }
; __device__ __forceinline__ void phase_gdn_solve(const Args& a, LAS unsigned char* lds, const WCtx& w, int l) {
;     ...
;             for (int i = 0; i < 32; i += 4) { const f32x4 sc = *(const LAS f32x4*)(BETA + 64 * wv + i);
; #pragma unroll
;                 for (int t = 0; t < 4; ++t) x[i + t] *= sc[t]; }
;             solve_diag(x, A11T, 0, 0, 16);
.LBB0_1062:
	s_and_b64 vcc, exec, s[0:1]
	s_waitcnt lgkmcnt(0)
	s_barrier
	s_cbranch_vccnz .LBB0_1043
	v_mov_b32_e32 v214, s39
	ds_read_b128 v[14:17], v214 offset:32512
	ds_read_b128 v[8:11], v214 offset:32528
	ds_read_b128 v[24:27], v214 offset:32544
	ds_read_b128 v[28:31], v214 offset:32560
	v_mov_b32_e32 v191, v137
	s_waitcnt lgkmcnt(3)
	v_pk_mul_f32 v[162:163], v[156:157], v[14:15] op_sel:[0,1] op_sel_hi:[1,0]
	v_mov_b32_e32 v157, s27
	ds_read_b128 v[4:7], v214 offset:32576
	ds_read_b128 v[18:21], v214 offset:32592
	ds_read_b128 v[38:41], v214 offset:32608
	ds_read_b128 v[12:15], v214 offset:32624
	ds_read_b128 v[54:57], v157 offset:9216
	ds_read_b128 v[72:75], v157 offset:9232
	ds_read_b128 v[46:49], v157 offset:9248
	ds_read_b128 v[32:35], v157 offset:9264
	s_waitcnt lgkmcnt(8)
	v_mov_b32_e32 v192, v31
	v_mov_b32_e32 v193, v28
	v_mov_b32_e32 v2, v29
	v_mov_b32_e32 v3, v30
	ds_read_b128 v[108:111], v157 offset:9280
	ds_read_b128 v[28:31], v157 offset:9296
	ds_read_b128 v[66:69], v157 offset:9312
	s_waitcnt lgkmcnt(3)
	v_mov_b32_e32 v22, v33
	v_mov_b32_e32 v23, v34
	v_mov_b32_e32 v137, v139
	v_pk_mul_f32 v[22:23], v[162:163], v[22:23] op_sel:[1,0]
	v_fma_f32 v156, -v163, v55, v162
	v_pk_fma_f32 v[188:189], v[136:137], v[2:3], v[22:23] neg_lo:[0,0,1] neg_hi:[0,0,1]
	v_mov_b32_e32 v2, v35
	v_mov_b32_e32 v3, v32
	v_pk_mul_f32 v[200:201], v[162:163], v[2:3] op_sel:[1,0]
	s_waitcnt lgkmcnt(0)
	v_pk_mul_f32 v[2:3], v[162:163], v[66:67] op_sel:[1,0]
	v_mov_b32_e32 v190, v138
	v_pk_fma_f32 v[206:207], v[64:65], v[38:39], v[2:3] op_sel:[1,0,0] op_sel_hi:[0,1,1] neg_lo:[0,0,1] neg_hi:[0,0,1]
	v_mov_b32_e32 v2, v51
	ds_read_b128 v[36:39], v157 offset:9328
	ds_read_b128 v[88:91], v157 offset:9376
	ds_read_b128 v[76:79], v157 offset:9392
	ds_read_b128 v[52:55], v157 offset:9408
	v_lshl_add_u32 v22, v2, 2, s27
	v_pk_mul_f32 v[2:3], v[162:163], v[56:57] op_sel:[1,0]
	ds_read_b128 v[116:119], v157 offset:9424
	ds_read_b128 v[32:35], v157 offset:9440
	ds_read_b128 v[80:83], v157 offset:9456
	ds_read_b128 v[112:115], v157 offset:9472
	ds_read_b128 v[64:67], v22 offset:9504
	ds_read_b128 v[98:101], v22 offset:9520
	ds_read_b128 v[84:87], v22 offset:9536
	ds_read_b128 v[42:45], v22 offset:9552
	v_pk_fma_f32 v[2:3], v[152:153], v[16:17], v[2:3] op_sel:[1,0,0] op_sel_hi:[0,1,1] neg_lo:[0,0,1] neg_hi:[0,0,1]
	ds_read_b64 v[16:17], v157 offset:9368
	ds_read_b128 v[128:131], v22 offset:9568
	ds_read_b128 v[56:59], v22 offset:9584
	ds_read_b128 v[92:95], v22 offset:9600
	ds_read_b128 v[136:139], v22 offset:9616
	v_mov_b32_e32 v97, v123
	v_mov_b32_e32 v123, v124
	s_waitcnt lgkmcnt(4)
	v_pk_fma_f32 v[164:165], v[156:157], v[16:17], v[2:3] op_sel_hi:[0,1,1] neg_lo:[1,0,0] neg_hi:[1,0,0]
	v_pk_mul_f32 v[2:3], v[162:163], v[68:69] op_sel:[1,0]
	v_fma_f32 v152, -v164, v67, v165
	v_pk_fma_f32 v[2:3], v[62:63], v[40:41], v[2:3] op_sel:[1,0,0] op_sel_hi:[0,1,1] neg_lo:[0,0,1] neg_hi:[0,0,1]
	v_pk_fma_f32 v[2:3], v[156:157], v[82:83], v[2:3] op_sel_hi:[0,1,1] neg_lo:[1,0,0] neg_hi:[1,0,0]
	s_waitcnt lgkmcnt(1)
	v_pk_fma_f32 v[194:195], v[164:165], v[94:95], v[2:3] op_sel_hi:[0,1,1] neg_lo:[1,0,0] neg_hi:[1,0,0]
	v_mov_b32_e32 v2, v51
	v_mov_b32_e32 v17, v72
	v_lshl_add_u32 v16, v2, 2, s27
	ds_read_b128 v[132:135], v16 offset:9664
	ds_read_b128 v[102:105], v16 offset:9680
	ds_read_b128 v[68:71], v16 offset:9696
	ds_read_b128 v[166:169], v16 offset:9712
	v_pk_mul_f32 v[2:3], v[162:163], v[108:109] op_sel:[1,0]
	v_pk_mul_f32 v[40:41], v[162:163], v[110:111] op_sel:[1,0]
	v_pk_fma_f32 v[2:3], v[60:61], v[4:5], v[2:3] op_sel:[1,0,0] op_sel_hi:[0,1,1] neg_lo:[0,0,1] neg_hi:[0,0,1]
	v_pk_fma_f32 v[2:3], v[156:157], v[116:117], v[2:3] op_sel_hi:[0,1,1] neg_lo:[1,0,0] neg_hi:[1,0,0]
	v_pk_fma_f32 v[2:3], v[164:165], v[128:129], v[2:3] op_sel_hi:[0,1,1] neg_lo:[1,0,0] neg_hi:[1,0,0]
	s_waitcnt lgkmcnt(0)
	v_pk_fma_f32 v[174:175], v[152:153], v[166:167], v[2:3] op_sel_hi:[0,1,1] neg_lo:[1,0,0] neg_hi:[1,0,0]
	v_mov_b32_e32 v2, v51
	ds_read_b128 v[60:63], v16 offset:9728
	ds_read_b128 v[64:67], v16 offset:9744
	ds_read_b128 v[170:173], v16 offset:9760
	v_mov_b32_e32 v16, v75
	v_lshl_add_u32 v22, v2, 2, s27
	v_mov_b32_e32 v2, v158
	v_mov_b32_e32 v3, v155
	v_mov_b32_e32 v4, v11
	v_mov_b32_e32 v5, v8
	v_pk_mul_f32 v[16:17], v[162:163], v[16:17] op_sel:[1,0]
	v_mov_b32_e32 v155, v159
	v_pk_fma_f32 v[2:3], v[2:3], v[4:5], v[16:17] neg_lo:[0,0,1] neg_hi:[0,0,1]
	v_mov_b32_e32 v4, v91
	v_mov_b32_e32 v5, v88
	v_pk_fma_f32 v[2:3], v[156:157], v[4:5], v[2:3] op_sel_hi:[0,1,1] neg_lo:[1,0,0] neg_hi:[1,0,0]
	v_mov_b32_e32 v4, v101
	v_mov_b32_e32 v5, v98
	v_pk_fma_f32 v[2:3], v[164:165], v[4:5], v[2:3] op_sel_hi:[0,1,1] neg_lo:[1,0,0] neg_hi:[1,0,0]
	v_mov_b32_e32 v4, v135
	v_mov_b32_e32 v5, v132
	v_pk_fma_f32 v[166:167], v[152:153], v[4:5], v[2:3] op_sel_hi:[0,1,1] neg_lo:[1,0,0] neg_hi:[1,0,0]
	v_mov_b32_e32 v4, v73
	v_mov_b32_e32 v5, v74
	v_mov_b32_e32 v2, v9
	v_mov_b32_e32 v3, v10
	v_pk_mul_f32 v[4:5], v[162:163], v[4:5] op_sel:[1,0]
	v_pk_fma_f32 v[6:7], v[120:121], v[6:7], v[40:41] op_sel:[1,0,0] op_sel_hi:[0,1,1] neg_lo:[0,0,1] neg_hi:[0,0,1]
	v_pk_fma_f32 v[2:3], v[154:155], v[2:3], v[4:5] neg_lo:[0,0,1] neg_hi:[0,0,1]
	v_mov_b32_e32 v4, v89
	v_mov_b32_e32 v5, v90
	v_pk_fma_f32 v[2:3], v[156:157], v[4:5], v[2:3] op_sel_hi:[0,1,1] neg_lo:[1,0,0] neg_hi:[1,0,0]
	v_mov_b32_e32 v4, v99
	v_mov_b32_e32 v5, v100
	v_pk_fma_f32 v[2:3], v[164:165], v[4:5], v[2:3] op_sel_hi:[0,1,1] neg_lo:[1,0,0] neg_hi:[1,0,0]
	v_mov_b32_e32 v4, v133
	v_mov_b32_e32 v5, v134
	v_pk_fma_f32 v[16:17], v[152:153], v[4:5], v[2:3] op_sel_hi:[0,1,1] neg_lo:[1,0,0] neg_hi:[1,0,0]
	ds_read_b128 v[8:11], v22 offset:9808
	ds_read_b128 v[106:109], v22 offset:9824
	ds_read_b128 v[88:91], v22 offset:9840
	ds_read_b128 v[2:5], v22 offset:9856
	ds_read_b128 v[140:143], v22 offset:9872
	ds_read_b128 v[72:75], v22 offset:9888
	ds_read_b128 v[178:181], v22 offset:9904
	s_waitcnt lgkmcnt(6)
; #define LAS __attribute__((address_space(3)))
; __device__ __forceinline__ void solve_diag(float (&x)[64], const LAS float* AT, const int o, const int ja, const int jb) {
; #pragma unroll
;     for (int j = ja; j < jb; ++j) { const float xj = x[o + j];
;         int z = 0; if (j >= 2) asm("" : "+v"(z) : "v"(x[o + j - 2]));
;         const LAS float* ATj = AT + z;
; #pragma unroll
;         for (int i4 = ((j + 1) >> 2) << 2; i4 < 32; i4 += 4) { const f32x4 av = *(const LAS f32x4*)(ATj + j * 36 + i4);
; #pragma unroll
;             for (int t = 0; t < 4; ++t) if (i4 + t > j) x[o + i4 + t] -= av[t] * xj; } }
	v_mov_b32_e32 v8, v9
	v_mov_b32_e32 v9, v10
	v_pk_fma_f32 v[154:155], v[166:167], v[8:9], v[16:17] op_sel:[1,0,0] neg_lo:[1,0,0] neg_hi:[1,0,0]
	v_fma_f32 v17, -v167, v11, v166
	v_mov_b32_e32 v10, v39
	v_mov_b32_e32 v11, v36
	v_mov_b32_e32 v8, v15
	v_mov_b32_e32 v9, v12
	v_pk_mul_f32 v[10:11], v[162:163], v[10:11] op_sel:[1,0]
	v_pk_fma_f32 v[6:7], v[156:157], v[118:119], v[6:7] op_sel_hi:[0,1,1] neg_lo:[1,0,0] neg_hi:[1,0,0]
	v_pk_fma_f32 v[8:9], v[96:97], v[8:9], v[10:11] neg_lo:[0,0,1] neg_hi:[0,0,1]
	v_mov_b32_e32 v10, v115
	v_mov_b32_e32 v11, v112
	v_pk_fma_f32 v[8:9], v[156:157], v[10:11], v[8:9] op_sel_hi:[0,1,1] neg_lo:[1,0,0] neg_hi:[1,0,0]
	v_mov_b32_e32 v10, v139
	v_mov_b32_e32 v11, v136
	v_pk_fma_f32 v[8:9], v[164:165], v[10:11], v[8:9] op_sel_hi:[0,1,1] neg_lo:[1,0,0] neg_hi:[1,0,0]
	v_mov_b32_e32 v10, v173
	v_mov_b32_e32 v11, v170
	v_pk_fma_f32 v[8:9], v[152:153], v[10:11], v[8:9] op_sel_hi:[0,1,1] neg_lo:[1,0,0] neg_hi:[1,0,0]
	s_waitcnt lgkmcnt(0)
	v_mov_b32_e32 v10, v181
	v_mov_b32_e32 v11, v178
	v_pk_fma_f32 v[204:205], v[166:167], v[10:11], v[8:9] op_sel:[1,0,0] neg_lo:[1,0,0] neg_hi:[1,0,0]
	v_mov_b32_e32 v8, v51
	v_pk_fma_f32 v[6:7], v[164:165], v[130:131], v[6:7] op_sel_hi:[0,1,1] neg_lo:[1,0,0] neg_hi:[1,0,0]
	v_lshl_add_u32 v12, v8, 2, s27
	ds_read_b64 v[22:23], v12 offset:9960
	ds_read_b128 v[132:135], v12 offset:9968
	ds_read_b128 v[98:101], v12 offset:9984
	ds_read_b128 v[8:11], v12 offset:10000
	ds_read_b128 v[144:147], v12 offset:10016
	v_pk_fma_f32 v[6:7], v[152:153], v[168:169], v[6:7] op_sel_hi:[0,1,1] neg_lo:[1,0,0] neg_hi:[1,0,0]
	v_pk_fma_f32 v[4:5], v[166:167], v[4:5], v[6:7] op_sel:[1,0,0] neg_lo:[1,0,0] neg_hi:[1,0,0]
	v_mov_b32_e32 v16, v155
	s_waitcnt lgkmcnt(1)
	v_pk_fma_f32 v[176:177], v[154:155], v[10:11], v[4:5] op_sel_hi:[0,1,1] neg_lo:[1,0,0] neg_hi:[1,0,0]
	ds_read_b128 v[94:97], v12 offset:10032
	ds_read_b128 v[4:7], v12 offset:10048
	v_mov_b32_e32 v10, v13
	v_mov_b32_e32 v12, v37
	v_mov_b32_e32 v13, v38
	v_mov_b32_e32 v11, v14
	v_pk_mul_f32 v[12:13], v[162:163], v[12:13] op_sel:[1,0]
	s_waitcnt lgkmcnt(0)
	v_mov_b32_e32 v209, v4
	v_pk_fma_f32 v[10:11], v[122:123], v[10:11], v[12:13] neg_lo:[0,0,1] neg_hi:[0,0,1]
	v_mov_b32_e32 v12, v113
	v_mov_b32_e32 v13, v114
	v_pk_fma_f32 v[10:11], v[156:157], v[12:13], v[10:11] op_sel_hi:[0,1,1] neg_lo:[1,0,0] neg_hi:[1,0,0]
	v_mov_b32_e32 v12, v137
	v_mov_b32_e32 v13, v138
	v_pk_fma_f32 v[10:11], v[164:165], v[12:13], v[10:11] op_sel_hi:[0,1,1] neg_lo:[1,0,0] neg_hi:[1,0,0]
	v_mov_b32_e32 v12, v171
	v_mov_b32_e32 v13, v172
	v_pk_fma_f32 v[10:11], v[152:153], v[12:13], v[10:11] op_sel_hi:[0,1,1] neg_lo:[1,0,0] neg_hi:[1,0,0]
	v_mov_b32_e32 v12, v179
	v_mov_b32_e32 v13, v180
	v_mov_b32_e32 v4, v51
	v_pk_fma_f32 v[10:11], v[166:167], v[12:13], v[10:11] op_sel:[1,0,0] neg_lo:[1,0,0] neg_hi:[1,0,0]
	v_mov_b32_e32 v12, v5
	v_mov_b32_e32 v13, v6
	v_pk_fma_f32 v[180:181], v[154:155], v[12:13], v[10:11] op_sel_hi:[0,1,1] neg_lo:[1,0,0] neg_hi:[1,0,0]
	v_lshl_add_u32 v14, v4, 2, s27
	v_mov_b32_e32 v208, v7
	ds_read_b128 v[10:13], v14 offset:10096
	ds_read_b128 v[170:173], v14 offset:10112
	ds_read_b128 v[110:113], v14 offset:10128
	ds_read_b128 v[4:7], v14 offset:10144
	v_pk_fma_f32 v[168:169], v[154:155], v[22:23], v[16:17] op_sel_hi:[0,1,1] neg_lo:[1,0,0] neg_hi:[1,0,0]
	v_mov_b32_e32 v22, v31
	v_mov_b32_e32 v23, v28
	ds_read_b128 v[182:185], v14 offset:10160
	ds_read_b128 v[114:117], v14 offset:10176
	ds_read_b128 v[128:131], v14 offset:10192
	s_waitcnt lgkmcnt(6)
	v_mov_b32_e32 v10, v51
	v_mov_b32_e32 v14, v160
	v_mov_b32_e32 v15, v127
	v_mov_b32_e32 v16, v21
	v_mov_b32_e32 v17, v18
	v_pk_mul_f32 v[22:23], v[162:163], v[22:23] op_sel:[1,0]
	v_fma_f32 v158, -v168, v13, v169
	v_lshl_add_u32 v36, v10, 2, s27
	v_pk_fma_f32 v[14:15], v[14:15], v[16:17], v[22:23] neg_lo:[0,0,1] neg_hi:[0,0,1]
	v_mov_b32_e32 v16, v35
	v_mov_b32_e32 v17, v32
	ds_read_b128 v[216:219], v36 offset:10256
	ds_read_b128 v[122:125], v36 offset:10272
	ds_read_b128 v[10:13], v36 offset:10288
	ds_read_b128 v[220:223], v36 offset:10304
	v_pk_fma_f32 v[14:15], v[156:157], v[16:17], v[14:15] op_sel_hi:[0,1,1] neg_lo:[1,0,0] neg_hi:[1,0,0]
	v_mov_b32_e32 v16, v59
	v_mov_b32_e32 v17, v56
	v_pk_fma_f32 v[14:15], v[164:165], v[16:17], v[14:15] op_sel_hi:[0,1,1] neg_lo:[1,0,0] neg_hi:[1,0,0]
	v_mov_b32_e32 v16, v63
	v_mov_b32_e32 v17, v60
	v_pk_fma_f32 v[14:15], v[152:153], v[16:17], v[14:15] op_sel_hi:[0,1,1] neg_lo:[1,0,0] neg_hi:[1,0,0]
	v_mov_b32_e32 v16, v143
	v_mov_b32_e32 v17, v140
	v_pk_fma_f32 v[14:15], v[166:167], v[16:17], v[14:15] op_sel:[1,0,0] neg_lo:[1,0,0] neg_hi:[1,0,0]
	v_mov_b32_e32 v16, v147
	v_mov_b32_e32 v17, v144
	v_pk_fma_f32 v[14:15], v[154:155], v[16:17], v[14:15] op_sel_hi:[0,1,1] neg_lo:[1,0,0] neg_hi:[1,0,0]
	s_waitcnt lgkmcnt(6)
	v_mov_b32_e32 v16, v185
	v_mov_b32_e32 v17, v182
	v_mov_b32_e32 v18, v19
	v_mov_b32_e32 v19, v20
	v_mov_b32_e32 v20, v29
	v_mov_b32_e32 v21, v30
	v_pk_fma_f32 v[14:15], v[168:169], v[16:17], v[14:15] op_sel_hi:[0,1,1] neg_lo:[1,0,0] neg_hi:[1,0,0]
	s_waitcnt lgkmcnt(0)
; #define LAS __attribute__((address_space(3)))
; __device__ __forceinline__ void solve_diag(float (&x)[64], const LAS float* AT, const int o, const int ja, const int jb) {
; #pragma unroll
;     for (int j = ja; j < jb; ++j) { const float xj = x[o + j];
;         int z = 0; if (j >= 2) asm("" : "+v"(z) : "v"(x[o + j - 2]));
;         const LAS float* ATj = AT + z;
; #pragma unroll
;         for (int i4 = ((j + 1) >> 2) << 2; i4 < 32; i4 += 4) { const f32x4 av = *(const LAS f32x4*)(ATj + j * 36 + i4);
; #pragma unroll
;             for (int t = 0; t < 4; ++t) if (i4 + t > j) x[o + i4 + t] -= av[t] * xj; } }
	v_mov_b32_e32 v16, v223
	v_mov_b32_e32 v17, v220
	v_pk_mul_f32 v[22:23], v[162:163], v[46:47] op_sel:[1,0]
	v_mov_b32_e32 v127, v161
	v_pk_mul_f32 v[20:21], v[162:163], v[20:21] op_sel:[1,0]
	v_pk_fma_f32 v[178:179], v[158:159], v[16:17], v[14:15] op_sel_hi:[0,1,1] neg_lo:[1,0,0] neg_hi:[1,0,0]
	v_mov_b32_e32 v14, v51
	v_pk_fma_f32 v[22:23], v[148:149], v[24:25], v[22:23] op_sel:[1,0,0] op_sel_hi:[0,1,1] neg_lo:[0,0,1] neg_hi:[0,0,1]
	v_pk_fma_f32 v[18:19], v[126:127], v[18:19], v[20:21] neg_lo:[0,0,1] neg_hi:[0,0,1]
	v_mov_b32_e32 v20, v33
	v_mov_b32_e32 v21, v34
	v_pk_fma_f32 v[22:23], v[156:157], v[76:77], v[22:23] op_sel_hi:[0,1,1] neg_lo:[1,0,0] neg_hi:[1,0,0]
	v_lshl_add_u32 v28, v14, 2, s27
	v_pk_fma_f32 v[18:19], v[156:157], v[20:21], v[18:19] op_sel_hi:[0,1,1] neg_lo:[1,0,0] neg_hi:[1,0,0]
	v_mov_b32_e32 v20, v57
	v_mov_b32_e32 v21, v58
	ds_read_b128 v[118:121], v36 offset:10320
	ds_read_b128 v[38:41], v36 offset:10336
	ds_read_b128 v[242:245], v28 offset:10400
	ds_read_b128 v[136:139], v28 offset:10416
	ds_read_b128 v[14:17], v28 offset:10432
	ds_read_b128 v[246:249], v28 offset:10448
	v_pk_fma_f32 v[22:23], v[164:165], v[84:85], v[22:23] op_sel_hi:[0,1,1] neg_lo:[1,0,0] neg_hi:[1,0,0]
	v_pk_fma_f32 v[18:19], v[164:165], v[20:21], v[18:19] op_sel_hi:[0,1,1] neg_lo:[1,0,0] neg_hi:[1,0,0]
	v_mov_b32_e32 v20, v61
	v_mov_b32_e32 v21, v62
	v_pk_fma_f32 v[22:23], v[152:153], v[102:103], v[22:23] op_sel_hi:[0,1,1] neg_lo:[1,0,0] neg_hi:[1,0,0]
	v_pk_fma_f32 v[18:19], v[152:153], v[20:21], v[18:19] op_sel_hi:[0,1,1] neg_lo:[1,0,0] neg_hi:[1,0,0]
	v_mov_b32_e32 v20, v141
	v_mov_b32_e32 v21, v142
	v_pk_fma_f32 v[22:23], v[166:167], v[106:107], v[22:23] op_sel:[1,0,0] neg_lo:[1,0,0] neg_hi:[1,0,0]
	v_pk_fma_f32 v[18:19], v[166:167], v[20:21], v[18:19] op_sel:[1,0,0] neg_lo:[1,0,0] neg_hi:[1,0,0]
	v_mov_b32_e32 v20, v145
	v_mov_b32_e32 v21, v146
	v_pk_fma_f32 v[22:23], v[154:155], v[132:133], v[22:23] op_sel_hi:[0,1,1] neg_lo:[1,0,0] neg_hi:[1,0,0]
	v_pk_fma_f32 v[18:19], v[154:155], v[20:21], v[18:19] op_sel_hi:[0,1,1] neg_lo:[1,0,0] neg_hi:[1,0,0]
	v_mov_b32_e32 v20, v183
	v_mov_b32_e32 v21, v184
	v_pk_fma_f32 v[22:23], v[168:169], v[170:171], v[22:23] op_sel_hi:[0,1,1] neg_lo:[1,0,0] neg_hi:[1,0,0]
	v_pk_fma_f32 v[18:19], v[168:169], v[20:21], v[18:19] op_sel_hi:[0,1,1] neg_lo:[1,0,0] neg_hi:[1,0,0]
	v_mov_b32_e32 v20, v221
	v_mov_b32_e32 v21, v222
	v_pk_fma_f32 v[170:171], v[158:159], v[216:217], v[22:23] op_sel_hi:[0,1,1] neg_lo:[1,0,0] neg_hi:[1,0,0]
	v_pk_fma_f32 v[18:19], v[158:159], v[20:21], v[18:19] op_sel_hi:[0,1,1] neg_lo:[1,0,0] neg_hi:[1,0,0]
	s_waitcnt lgkmcnt(0)
	v_mov_b32_e32 v20, v247
	v_mov_b32_e32 v21, v248
	v_pk_fma_f32 v[160:161], v[170:171], v[20:21], v[18:19] op_sel_hi:[0,1,1] neg_lo:[1,0,0] neg_hi:[1,0,0]
	v_mov_b32_e32 v18, v51
	v_pk_mul_f32 v[46:47], v[162:163], v[48:49] op_sel:[1,0]
	v_lshl_add_u32 v18, v18, 2, s27
	v_pk_fma_f32 v[26:27], v[150:151], v[26:27], v[46:47] op_sel:[1,0,0] op_sel_hi:[0,1,1] neg_lo:[0,0,1] neg_hi:[0,0,1]
	ds_read_b128 v[140:143], v28 offset:10464
	ds_read_b128 v[56:59], v28 offset:10480
	ds_read_b64 v[28:29], v18 offset:10552
	ds_read_b128 v[220:223], v18 offset:10560
	ds_read_b128 v[30:33], v18 offset:10576
	ds_read_b128 v[22:25], v18 offset:10592
	ds_read_b128 v[144:147], v18 offset:10608
	v_pk_fma_f32 v[26:27], v[156:157], v[78:79], v[26:27] op_sel_hi:[0,1,1] neg_lo:[1,0,0] neg_hi:[1,0,0]
	v_pk_fma_f32 v[26:27], v[164:165], v[86:87], v[26:27] op_sel_hi:[0,1,1] neg_lo:[1,0,0] neg_hi:[1,0,0]
	v_pk_fma_f32 v[26:27], v[152:153], v[104:105], v[26:27] op_sel_hi:[0,1,1] neg_lo:[1,0,0] neg_hi:[1,0,0]
	ds_read_b128 v[60:63], v18 offset:10624
	v_mov_b32_e32 v18, v51
	v_pk_fma_f32 v[26:27], v[166:167], v[108:109], v[26:27] op_sel:[1,0,0] neg_lo:[1,0,0] neg_hi:[1,0,0]
	v_pk_fma_f32 v[80:81], v[156:157], v[80:81], v[206:207] op_sel_hi:[0,1,1] neg_lo:[1,0,0] neg_hi:[1,0,0]
	s_waitcnt lgkmcnt(2)
	v_mov_b32_e32 v182, v23
	v_pk_fma_f32 v[26:27], v[154:155], v[134:135], v[26:27] op_sel_hi:[0,1,1] neg_lo:[1,0,0] neg_hi:[1,0,0]
	v_lshl_add_u32 v23, v18, 2, s27
	v_pk_fma_f32 v[80:81], v[164:165], v[92:93], v[80:81] op_sel_hi:[0,1,1] neg_lo:[1,0,0] neg_hi:[1,0,0]
	v_mov_b32_e32 v184, v249
	v_mov_b32_e32 v185, v246
	ds_read_b128 v[82:85], v23 offset:10688
	ds_read_b128 v[246:249], v23 offset:10704
	ds_read_b128 v[34:37], v23 offset:10720
	ds_read_b128 v[18:21], v23 offset:10736
	v_pk_fma_f32 v[26:27], v[168:169], v[172:173], v[26:27] op_sel_hi:[0,1,1] neg_lo:[1,0,0] neg_hi:[1,0,0]
	ds_read_b128 v[102:105], v23 offset:10752
	ds_read_b128 v[76:79], v23 offset:10768
	v_mov_b32_e32 v23, v51
	v_pk_fma_f32 v[64:65], v[152:153], v[64:65], v[80:81] op_sel_hi:[0,1,1] neg_lo:[1,0,0] neg_hi:[1,0,0]
	v_fma_f32 v148, -v170, v243, v171
	v_pk_fma_f32 v[26:27], v[158:159], v[218:219], v[26:27] op_sel_hi:[0,1,1] neg_lo:[1,0,0] neg_hi:[1,0,0]
	v_pk_fma_f32 v[64:65], v[166:167], v[72:73], v[64:65] op_sel:[1,0,0] neg_lo:[1,0,0] neg_hi:[1,0,0]
	v_pk_fma_f32 v[26:27], v[170:171], v[244:245], v[26:27] op_sel_hi:[0,1,1] neg_lo:[1,0,0] neg_hi:[1,0,0]
	v_lshl_add_u32 v23, v23, 2, s27
	v_pk_fma_f32 v[64:65], v[154:155], v[94:95], v[64:65] op_sel_hi:[0,1,1] neg_lo:[1,0,0] neg_hi:[1,0,0]
	v_pk_fma_f32 v[172:173], v[148:149], v[28:29], v[26:27] op_sel_hi:[0,1,1] neg_lo:[1,0,0] neg_hi:[1,0,0]
	ds_read_b128 v[106:109], v23 offset:10848
	ds_read_b128 v[46:49], v23 offset:10864
	ds_read_b128 v[26:29], v23 offset:10880
	ds_read_b128 v[132:135], v23 offset:10896
	v_pk_fma_f32 v[64:65], v[168:169], v[114:115], v[64:65] op_sel_hi:[0,1,1] neg_lo:[1,0,0] neg_hi:[1,0,0]
	v_pk_fma_f32 v[64:65], v[158:159], v[118:119], v[64:65] op_sel_hi:[0,1,1] neg_lo:[1,0,0] neg_hi:[1,0,0]
	v_pk_fma_f32 v[64:65], v[170:171], v[140:141], v[64:65] op_sel_hi:[0,1,1] neg_lo:[1,0,0] neg_hi:[1,0,0]
	s_waitcnt lgkmcnt(11)
; #define LAS __attribute__((address_space(3)))
; __device__ __forceinline__ void solve_diag(float (&x)[64], const LAS float* AT, const int o, const int ja, const int jb) {
; #pragma unroll
;     for (int j = ja; j < jb; ++j) { const float xj = x[o + j];
;         int z = 0; if (j >= 2) asm("" : "+v"(z) : "v"(x[o + j - 2]));
;         const LAS float* ATj = AT + z;
; #pragma unroll
;         for (int i4 = ((j + 1) >> 2) << 2; i4 < 32; i4 += 4) { const f32x4 av = *(const LAS f32x4*)(ATj + j * 36 + i4);
; #pragma unroll
;             for (int t = 0; t < 4; ++t) if (i4 + t > j) x[o + i4 + t] -= av[t] * xj; } }
	v_pk_fma_f32 v[64:65], v[148:149], v[144:145], v[64:65] op_sel_hi:[0,1,1] neg_lo:[1,0,0] neg_hi:[1,0,0]
	s_waitcnt lgkmcnt(9)
	v_fma_f32 v150, -v172, v85, v173
	s_waitcnt lgkmcnt(5)
	v_pk_fma_f32 v[64:65], v[172:173], v[102:103], v[64:65] op_sel_hi:[0,1,1] neg_lo:[1,0,0] neg_hi:[1,0,0]
	v_mov_b32_e32 v203, v54
	s_waitcnt lgkmcnt(0)
	v_pk_fma_f32 v[144:145], v[150:151], v[132:133], v[64:65] op_sel_hi:[0,1,1] neg_lo:[1,0,0] neg_hi:[1,0,0]
	v_pk_fma_f32 v[64:65], v[190:191], v[192:193], v[200:201] neg_lo:[0,0,1] neg_hi:[0,0,1]
	v_mov_b32_e32 v54, v55
	v_mov_b32_e32 v55, v52
	v_mov_b32_e32 v202, v53
	v_pk_fma_f32 v[52:53], v[156:157], v[54:55], v[64:65] op_sel_hi:[0,1,1] neg_lo:[1,0,0] neg_hi:[1,0,0]
	v_mov_b32_e32 v54, v45
	v_mov_b32_e32 v55, v42
	v_pk_fma_f32 v[52:53], v[164:165], v[54:55], v[52:53] op_sel_hi:[0,1,1] neg_lo:[1,0,0] neg_hi:[1,0,0]
	v_mov_b32_e32 v54, v71
	v_mov_b32_e32 v55, v68
	v_pk_fma_f32 v[52:53], v[152:153], v[54:55], v[52:53] op_sel_hi:[0,1,1] neg_lo:[1,0,0] neg_hi:[1,0,0]
	v_mov_b32_e32 v54, v91
	v_mov_b32_e32 v55, v88
	v_pk_fma_f32 v[52:53], v[166:167], v[54:55], v[52:53] op_sel:[1,0,0] neg_lo:[1,0,0] neg_hi:[1,0,0]
	v_mov_b32_e32 v54, v101
	v_mov_b32_e32 v55, v98
	v_pk_fma_f32 v[52:53], v[154:155], v[54:55], v[52:53] op_sel_hi:[0,1,1] neg_lo:[1,0,0] neg_hi:[1,0,0]
	v_mov_b32_e32 v54, v113
	v_mov_b32_e32 v55, v110
	v_pk_fma_f32 v[52:53], v[168:169], v[54:55], v[52:53] op_sel_hi:[0,1,1] neg_lo:[1,0,0] neg_hi:[1,0,0]
	v_mov_b32_e32 v54, v125
	v_mov_b32_e32 v55, v122
	v_pk_fma_f32 v[52:53], v[158:159], v[54:55], v[52:53] op_sel_hi:[0,1,1] neg_lo:[1,0,0] neg_hi:[1,0,0]
	v_mov_b32_e32 v54, v139
	v_mov_b32_e32 v55, v136
	v_pk_fma_f32 v[52:53], v[170:171], v[54:55], v[52:53] op_sel_hi:[0,1,1] neg_lo:[1,0,0] neg_hi:[1,0,0]
	v_mov_b32_e32 v54, v223
	v_mov_b32_e32 v55, v220
	v_pk_fma_f32 v[52:53], v[148:149], v[54:55], v[52:53] op_sel_hi:[0,1,1] neg_lo:[1,0,0] neg_hi:[1,0,0]
	v_mov_b32_e32 v54, v249
	v_mov_b32_e32 v55, v246
	v_pk_fma_f32 v[52:53], v[172:173], v[54:55], v[52:53] op_sel_hi:[0,1,1] neg_lo:[1,0,0] neg_hi:[1,0,0]
	v_mov_b32_e32 v54, v109
	v_mov_b32_e32 v55, v106
	v_pk_fma_f32 v[140:141], v[150:151], v[54:55], v[52:53] op_sel_hi:[0,1,1] neg_lo:[1,0,0] neg_hi:[1,0,0]
	v_pk_fma_f32 v[52:53], v[156:157], v[202:203], v[188:189] op_sel_hi:[0,1,1] neg_lo:[1,0,0] neg_hi:[1,0,0]
	v_mov_b32_e32 v42, v43
	v_mov_b32_e32 v43, v44
	v_pk_fma_f32 v[42:43], v[164:165], v[42:43], v[52:53] op_sel_hi:[0,1,1] neg_lo:[1,0,0] neg_hi:[1,0,0]
	v_mov_b32_e32 v44, v69
	v_mov_b32_e32 v45, v70
	v_pk_fma_f32 v[42:43], v[152:153], v[44:45], v[42:43] op_sel_hi:[0,1,1] neg_lo:[1,0,0] neg_hi:[1,0,0]
	v_mov_b32_e32 v44, v89
	v_mov_b32_e32 v45, v90
	v_pk_fma_f32 v[42:43], v[166:167], v[44:45], v[42:43] op_sel:[1,0,0] neg_lo:[1,0,0] neg_hi:[1,0,0]
	v_mov_b32_e32 v44, v99
	v_mov_b32_e32 v45, v100
	v_pk_fma_f32 v[42:43], v[154:155], v[44:45], v[42:43] op_sel_hi:[0,1,1] neg_lo:[1,0,0] neg_hi:[1,0,0]
	v_mov_b32_e32 v44, v111
	v_mov_b32_e32 v45, v112
	v_pk_fma_f32 v[42:43], v[168:169], v[44:45], v[42:43] op_sel_hi:[0,1,1] neg_lo:[1,0,0] neg_hi:[1,0,0]
	v_mov_b32_e32 v44, v123
	v_mov_b32_e32 v45, v124
	v_pk_fma_f32 v[42:43], v[158:159], v[44:45], v[42:43] op_sel_hi:[0,1,1] neg_lo:[1,0,0] neg_hi:[1,0,0]
	v_mov_b32_e32 v44, v137
	v_mov_b32_e32 v45, v138
	ds_read_b128 v[84:87], v23 offset:10912
	v_mov_b32_e32 v23, v51
	v_pk_fma_f32 v[42:43], v[170:171], v[44:45], v[42:43] op_sel_hi:[0,1,1] neg_lo:[1,0,0] neg_hi:[1,0,0]
	v_mov_b32_e32 v44, v221
	v_mov_b32_e32 v45, v222
	v_pk_fma_f32 v[42:43], v[148:149], v[44:45], v[42:43] op_sel_hi:[0,1,1] neg_lo:[1,0,0] neg_hi:[1,0,0]
	v_mov_b32_e32 v44, v247
	v_mov_b32_e32 v45, v248
	v_lshl_add_u32 v23, v23, 2, s27
	v_pk_fma_f32 v[42:43], v[172:173], v[44:45], v[42:43] op_sel_hi:[0,1,1] neg_lo:[1,0,0] neg_hi:[1,0,0]
	v_mov_b32_e32 v44, v107
	v_mov_b32_e32 v45, v108
	v_pk_fma_f32 v[64:65], v[150:151], v[44:45], v[42:43] op_sel_hi:[0,1,1] neg_lo:[1,0,0] neg_hi:[1,0,0]
	ds_read_b128 v[52:55], v23 offset:10992
	ds_read_b128 v[92:95], v23 offset:11008
	ds_read_b128 v[68:71], v23 offset:11024
	ds_read_b128 v[42:45], v23 offset:11040
	ds_read_b128 v[108:111], v23 offset:11056
	s_waitcnt lgkmcnt(4)
	v_mov_b32_e32 v52, v53
	v_mov_b32_e32 v53, v54
	v_pk_fma_f32 v[136:137], v[140:141], v[52:53], v[64:65] op_sel:[1,0,0] neg_lo:[1,0,0] neg_hi:[1,0,0]
	v_pk_fma_f32 v[64:65], v[152:153], v[66:67], v[194:195] op_sel_hi:[0,1,1] neg_lo:[1,0,0] neg_hi:[1,0,0]
	v_pk_fma_f32 v[64:65], v[166:167], v[74:75], v[64:65] op_sel:[1,0,0] neg_lo:[1,0,0] neg_hi:[1,0,0]
	v_mov_b32_e32 v23, v51
	v_pk_fma_f32 v[64:65], v[154:155], v[96:97], v[64:65] op_sel_hi:[0,1,1] neg_lo:[1,0,0] neg_hi:[1,0,0]
	v_pk_fma_f32 v[64:65], v[168:169], v[116:117], v[64:65] op_sel_hi:[0,1,1] neg_lo:[1,0,0] neg_hi:[1,0,0]
	v_pk_fma_f32 v[64:65], v[158:159], v[120:121], v[64:65] op_sel_hi:[0,1,1] neg_lo:[1,0,0] neg_hi:[1,0,0]
	v_lshl_add_u32 v23, v23, 2, s27
	v_pk_fma_f32 v[64:65], v[170:171], v[142:143], v[64:65] op_sel_hi:[0,1,1] neg_lo:[1,0,0] neg_hi:[1,0,0]
	v_fma_f32 v99, -v141, v55, v140
	ds_read_b64 v[118:119], v23 offset:11144
	ds_read_b128 v[100:103], v23 offset:11152
	ds_read_b128 v[80:83], v23 offset:11168
	ds_read_b128 v[52:55], v23 offset:11184
	ds_read_b128 v[112:115], v23 offset:11200
	v_pk_fma_f32 v[64:65], v[148:149], v[146:147], v[64:65] op_sel_hi:[0,1,1] neg_lo:[1,0,0] neg_hi:[1,0,0]
	v_pk_fma_f32 v[64:65], v[172:173], v[104:105], v[64:65] op_sel_hi:[0,1,1] neg_lo:[1,0,0] neg_hi:[1,0,0]
	v_pk_fma_f32 v[64:65], v[150:151], v[134:135], v[64:65] op_sel_hi:[0,1,1] neg_lo:[1,0,0] neg_hi:[1,0,0]
	v_mov_b32_e32 v23, v51
	s_waitcnt lgkmcnt(6)
; #define LAS __attribute__((address_space(3)))
; __device__ __forceinline__ float bf2f(unsigned b) { return __uint_as_float(b << 16); }
; __device__ __forceinline__ void solve_diag(float (&x)[64], const LAS float* AT, const int o, const int ja, const int jb) {
; #pragma unroll
;     for (int j = ja; j < jb; ++j) { const float xj = x[o + j];
;         int z = 0; if (j >= 2) asm("" : "+v"(z) : "v"(x[o + j - 2]));
;         const LAS float* ATj = AT + z;
; #pragma unroll
;         for (int i4 = ((j + 1) >> 2) << 2; i4 < 32; i4 += 4) { const f32x4 av = *(const LAS f32x4*)(ATj + j * 36 + i4);
; #pragma unroll
;             for (int t = 0; t < 4; ++t) if (i4 + t > j) x[o + i4 + t] -= av[t] * xj; } }
; __device__ __forceinline__ void phase_gdn_solve(const Args& a, LAS unsigned char* lds, const WCtx& w, int l) {
;     ...
;             { long zz = 0; asm volatile("" : "+v"(zz) : "v"(x[15]));
;               const bf16* xp = PB + (size_t)row0 * NPB + (wv == 0 ? 512 : 256) + h * 64 + lane + zz;
; #pragma unroll
;               for (int i = 32; i < 64; ++i) x[i] = bf2f(xp[sg * i * NPB]); }
	v_pk_fma_f32 v[44:45], v[140:141], v[44:45], v[64:65] op_sel:[1,0,0] neg_lo:[1,0,0] neg_hi:[1,0,0]
	v_mov_b32_e32 v187, v130
	s_waitcnt lgkmcnt(1)
	v_pk_fma_f32 v[54:55], v[136:137], v[54:55], v[44:45] op_sel_hi:[0,1,1] neg_lo:[1,0,0] neg_hi:[1,0,0]
	v_lshl_add_u32 v23, v23, 2, s27
	v_pk_fma_f32 v[44:45], v[154:155], v[208:209], v[204:205] op_sel_hi:[0,1,1] neg_lo:[1,0,0] neg_hi:[1,0,0]
	v_mov_b32_e32 v130, v131
	v_mov_b32_e32 v131, v128
	v_mov_b32_e32 v186, v129
	ds_read_b128 v[72:75], v23 offset:11280
	ds_read_b128 v[104:107], v23 offset:11296
	ds_read_b128 v[88:91], v23 offset:11312
	ds_read_b128 v[64:67], v23 offset:11328
	ds_read_b128 v[120:123], v23 offset:11344
	v_mov_b32_e32 v23, v51
	v_pk_fma_f32 v[44:45], v[168:169], v[130:131], v[44:45] op_sel_hi:[0,1,1] neg_lo:[1,0,0] neg_hi:[1,0,0]
	v_mov_b32_e32 v128, v41
	v_mov_b32_e32 v129, v38
	v_mov_b32_e32 v98, v137
	v_pk_fma_f32 v[44:45], v[158:159], v[128:129], v[44:45] op_sel_hi:[0,1,1] neg_lo:[1,0,0] neg_hi:[1,0,0]
	v_mov_b32_e32 v128, v59
	v_mov_b32_e32 v129, v56
	v_pk_fma_f32 v[142:143], v[136:137], v[118:119], v[98:99] op_sel_hi:[0,1,1] neg_lo:[1,0,0] neg_hi:[1,0,0]
	v_lshl_add_u32 v23, v23, 2, s27
	v_pk_fma_f32 v[44:45], v[170:171], v[128:129], v[44:45] op_sel_hi:[0,1,1] neg_lo:[1,0,0] neg_hi:[1,0,0]
	v_mov_b32_e32 v128, v63
	v_mov_b32_e32 v129, v60
	s_waitcnt lgkmcnt(4)
	v_fma_f32 v138, -v142, v75, v143
	ds_read_b128 v[116:119], v23 offset:11440
	ds_read_b128 v[96:99], v23 offset:11456
	ds_read_b128 v[72:75], v23 offset:11472
	ds_read_b128 v[124:127], v23 offset:11488
	v_pk_fma_f32 v[44:45], v[148:149], v[128:129], v[44:45] op_sel_hi:[0,1,1] neg_lo:[1,0,0] neg_hi:[1,0,0]
	v_mov_b32_e32 v128, v79
	v_mov_b32_e32 v129, v76
	v_pk_fma_f32 v[44:45], v[172:173], v[128:129], v[44:45] op_sel_hi:[0,1,1] neg_lo:[1,0,0] neg_hi:[1,0,0]
	v_mov_b32_e32 v128, v87
	v_mov_b32_e32 v129, v84
	v_pk_fma_f32 v[44:45], v[150:151], v[128:129], v[44:45] op_sel_hi:[0,1,1] neg_lo:[1,0,0] neg_hi:[1,0,0]
	v_mov_b32_e32 v128, v111
	v_mov_b32_e32 v129, v108
	v_pk_fma_f32 v[44:45], v[140:141], v[128:129], v[44:45] op_sel:[1,0,0] neg_lo:[1,0,0] neg_hi:[1,0,0]
	v_mov_b32_e32 v128, v115
	v_mov_b32_e32 v129, v112
	s_add_u32 s0, s30, s71
	v_pk_fma_f32 v[44:45], v[136:137], v[128:129], v[44:45] op_sel_hi:[0,1,1] neg_lo:[1,0,0] neg_hi:[1,0,0]
	s_waitcnt lgkmcnt(4)
	v_mov_b32_e32 v128, v123
	v_mov_b32_e32 v129, v120
	s_addc_u32 s1, s31, s11
	s_lshl_b32 s2, s70, 7
	v_pk_fma_f32 v[44:45], v[142:143], v[128:129], v[44:45] op_sel_hi:[0,1,1] neg_lo:[1,0,0] neg_hi:[1,0,0]
	s_waitcnt lgkmcnt(0)
	v_mov_b32_e32 v128, v127
	v_mov_b32_e32 v129, v124
	s_add_u32 s0, s0, s2
	v_pk_fma_f32 v[146:147], v[138:139], v[128:129], v[44:45] op_sel_hi:[0,1,1] neg_lo:[1,0,0] neg_hi:[1,0,0]
	v_mov_b64_e32 v[44:45], 0
	s_addc_u32 s1, s1, 0
	v_lshl_add_u64 v[128:129], s[0:1], 0, v[50:51]
	v_lshl_add_u64 v[44:45], v[44:45], 1, v[128:129]
	v_mov_b32_e32 v23, 0x14000
	v_mad_u64_u32 v[44:45], s[0:1], s12, v23, v[44:45]
	s_mul_i32 s13, s13, 0x14000
	v_add_u32_e32 v45, s13, v45
	global_load_ushort v63, v[44:45], off
	v_mad_u64_u32 v[44:45], s[0:1], s12, v233, v[44:45]
	v_add_u32_e32 v45, s10, v45
	v_pk_fma_f32 v[2:3], v[166:167], v[2:3], v[174:175] op_sel:[1,0,0] neg_lo:[1,0,0] neg_hi:[1,0,0]
	v_pk_fma_f32 v[6:7], v[168:169], v[6:7], v[176:177] op_sel_hi:[0,1,1] neg_lo:[1,0,0] neg_hi:[1,0,0]
	v_pk_fma_f32 v[2:3], v[154:155], v[8:9], v[2:3] op_sel_hi:[0,1,1] neg_lo:[1,0,0] neg_hi:[1,0,0]
	v_pk_fma_f32 v[2:3], v[168:169], v[4:5], v[2:3] op_sel_hi:[0,1,1] neg_lo:[1,0,0] neg_hi:[1,0,0]
	v_mov_b32_e32 v4, v39
	v_mov_b32_e32 v5, v40
	v_mov_b32_e32 v183, v24
	s_mul_i32 s68, s68, 36
	s_and_b64 vcc, exec, s[4:5]
	global_load_ushort v84, v[44:45], off
	v_mad_u64_u32 v[44:45], s[0:1], s12, v233, v[44:45]
	v_add_u32_e32 v45, s10, v45
	global_load_ushort v87, v[44:45], off
	v_mad_u64_u32 v[44:45], s[0:1], s12, v233, v[44:45]
	v_add_u32_e32 v45, s10, v45
	global_load_ushort v108, v[44:45], off
	v_mad_u64_u32 v[44:45], s[0:1], s12, v233, v[44:45]
	v_add_u32_e32 v45, s10, v45
	global_load_ushort v111, v[44:45], off
	v_mad_u64_u32 v[44:45], s[0:1], s12, v233, v[44:45]
	v_add_u32_e32 v45, s10, v45
	global_load_ushort v112, v[44:45], off
	v_mad_u64_u32 v[44:45], s[0:1], s12, v233, v[44:45]
	v_add_u32_e32 v45, s10, v45
	global_load_ushort v115, v[44:45], off
	v_mad_u64_u32 v[44:45], s[0:1], s12, v233, v[44:45]
	v_add_u32_e32 v45, s10, v45
	global_load_ushort v139, v[44:45], off
	v_mad_u64_u32 v[44:45], s[0:1], s12, v233, v[44:45]
	v_add_u32_e32 v45, s10, v45
	global_load_ushort v149, v[44:45], off
	v_mad_u64_u32 v[44:45], s[0:1], s12, v233, v[44:45]
	v_add_u32_e32 v45, s10, v45
	global_load_ushort v151, v[44:45], off
	v_mad_u64_u32 v[44:45], s[0:1], s12, v233, v[44:45]
	v_add_u32_e32 v45, s10, v45
	global_load_ushort v153, v[44:45], off
	v_mad_u64_u32 v[44:45], s[0:1], s12, v233, v[44:45]
	v_add_u32_e32 v45, s10, v45
	global_load_ushort v159, v[44:45], off
	v_mad_u64_u32 v[44:45], s[0:1], s12, v233, v[44:45]
	v_add_u32_e32 v45, s10, v45
	global_load_ushort v162, v[44:45], off
	v_mad_u64_u32 v[44:45], s[0:1], s12, v233, v[44:45]
	v_add_u32_e32 v45, s10, v45
	v_pk_fma_f32 v[2:3], v[158:159], v[10:11], v[2:3] op_sel_hi:[0,1,1] neg_lo:[1,0,0] neg_hi:[1,0,0]
	v_pk_fma_f32 v[2:3], v[170:171], v[14:15], v[2:3] op_sel_hi:[0,1,1] neg_lo:[1,0,0] neg_hi:[1,0,0]
	v_pk_fma_f32 v[2:3], v[148:149], v[30:31], v[2:3] op_sel_hi:[0,1,1] neg_lo:[1,0,0] neg_hi:[1,0,0]
	v_pk_fma_f32 v[2:3], v[172:173], v[34:35], v[2:3] op_sel_hi:[0,1,1] neg_lo:[1,0,0] neg_hi:[1,0,0]
	v_pk_fma_f32 v[2:3], v[150:151], v[46:47], v[2:3] op_sel_hi:[0,1,1] neg_lo:[1,0,0] neg_hi:[1,0,0]
; #define LAS __attribute__((address_space(3)))
; __device__ __forceinline__ float bf2f(unsigned b) { return __uint_as_float(b << 16); }
; __device__ __forceinline__ void solve_diag(float (&x)[64], const LAS float* AT, const int o, const int ja, const int jb) {
; #pragma unroll
;     for (int j = ja; j < jb; ++j) { const float xj = x[o + j];
;         int z = 0; if (j >= 2) asm("" : "+v"(z) : "v"(x[o + j - 2]));
;         const LAS float* ATj = AT + z;
; #pragma unroll
;         for (int i4 = ((j + 1) >> 2) << 2; i4 < 32; i4 += 4) { const f32x4 av = *(const LAS f32x4*)(ATj + j * 36 + i4);
; #pragma unroll
;             for (int t = 0; t < 4; ++t) if (i4 + t > j) x[o + i4 + t] -= av[t] * xj; } }
; __device__ __forceinline__ void phase_gdn_solve(const Args& a, LAS unsigned char* lds, const WCtx& w, int l) {
;     ...
;             { long zz = 0; asm volatile("" : "+v"(zz) : "v"(x[15]));
;               const bf16* xp = PB + (size_t)row0 * NPB + (wv == 0 ? 512 : 256) + h * 64 + lane + zz;
; #pragma unroll
;               for (int i = 32; i < 64; ++i) x[i] = bf2f(xp[sg * i * NPB]); }
	v_pk_fma_f32 v[2:3], v[140:141], v[92:93], v[2:3] op_sel:[1,0,0] neg_lo:[1,0,0] neg_hi:[1,0,0]
	v_pk_fma_f32 v[6:7], v[158:159], v[12:13], v[6:7] op_sel_hi:[0,1,1] neg_lo:[1,0,0] neg_hi:[1,0,0]
	v_pk_fma_f32 v[2:3], v[136:137], v[100:101], v[2:3] op_sel_hi:[0,1,1] neg_lo:[1,0,0] neg_hi:[1,0,0]
	v_pk_fma_f32 v[2:3], v[142:143], v[104:105], v[2:3] op_sel_hi:[0,1,1] neg_lo:[1,0,0] neg_hi:[1,0,0]
	v_pk_fma_f32 v[92:93], v[138:139], v[116:117], v[2:3] op_sel_hi:[0,1,1] neg_lo:[1,0,0] neg_hi:[1,0,0]
	v_pk_fma_f32 v[2:3], v[168:169], v[186:187], v[180:181] op_sel_hi:[0,1,1] neg_lo:[1,0,0] neg_hi:[1,0,0]
	v_pk_fma_f32 v[2:3], v[158:159], v[4:5], v[2:3] op_sel_hi:[0,1,1] neg_lo:[1,0,0] neg_hi:[1,0,0]
	v_mov_b32_e32 v4, v57
	v_mov_b32_e32 v5, v58
	v_pk_fma_f32 v[2:3], v[170:171], v[4:5], v[2:3] op_sel_hi:[0,1,1] neg_lo:[1,0,0] neg_hi:[1,0,0]
	v_mov_b32_e32 v4, v61
	v_mov_b32_e32 v5, v62
	v_pk_fma_f32 v[2:3], v[148:149], v[4:5], v[2:3] op_sel_hi:[0,1,1] neg_lo:[1,0,0] neg_hi:[1,0,0]
	v_mov_b32_e32 v4, v77
	v_mov_b32_e32 v5, v78
	v_pk_fma_f32 v[2:3], v[172:173], v[4:5], v[2:3] op_sel_hi:[0,1,1] neg_lo:[1,0,0] neg_hi:[1,0,0]
	v_mov_b32_e32 v4, v85
	v_mov_b32_e32 v5, v86
	v_pk_fma_f32 v[2:3], v[150:151], v[4:5], v[2:3] op_sel_hi:[0,1,1] neg_lo:[1,0,0] neg_hi:[1,0,0]
	v_mov_b32_e32 v4, v109
	v_mov_b32_e32 v5, v110
	v_pk_fma_f32 v[2:3], v[140:141], v[4:5], v[2:3] op_sel:[1,0,0] neg_lo:[1,0,0] neg_hi:[1,0,0]
	v_mov_b32_e32 v4, v113
	v_mov_b32_e32 v5, v114
	v_pk_fma_f32 v[2:3], v[136:137], v[4:5], v[2:3] op_sel_hi:[0,1,1] neg_lo:[1,0,0] neg_hi:[1,0,0]
	v_mov_b32_e32 v4, v121
	v_mov_b32_e32 v5, v122
	v_pk_fma_f32 v[2:3], v[142:143], v[4:5], v[2:3] op_sel_hi:[0,1,1] neg_lo:[1,0,0] neg_hi:[1,0,0]
	v_mov_b32_e32 v4, v125
	v_mov_b32_e32 v5, v126
	v_pk_fma_f32 v[6:7], v[170:171], v[16:17], v[6:7] op_sel_hi:[0,1,1] neg_lo:[1,0,0] neg_hi:[1,0,0]
	v_pk_fma_f32 v[2:3], v[138:139], v[4:5], v[2:3] op_sel_hi:[0,1,1] neg_lo:[1,0,0] neg_hi:[1,0,0]
	v_pk_fma_f32 v[6:7], v[148:149], v[32:33], v[6:7] op_sel_hi:[0,1,1] neg_lo:[1,0,0] neg_hi:[1,0,0]
	v_pk_fma_f32 v[6:7], v[172:173], v[36:37], v[6:7] op_sel_hi:[0,1,1] neg_lo:[1,0,0] neg_hi:[1,0,0]
	v_pk_fma_f32 v[6:7], v[150:151], v[48:49], v[6:7] op_sel_hi:[0,1,1] neg_lo:[1,0,0] neg_hi:[1,0,0]
	v_pk_fma_f32 v[6:7], v[140:141], v[94:95], v[6:7] op_sel:[1,0,0] neg_lo:[1,0,0] neg_hi:[1,0,0]
	v_mov_b32_e32 v16, v25
	v_pk_fma_f32 v[6:7], v[136:137], v[102:103], v[6:7] op_sel_hi:[0,1,1] neg_lo:[1,0,0] neg_hi:[1,0,0]
	v_pk_fma_f32 v[6:7], v[142:143], v[106:107], v[6:7] op_sel_hi:[0,1,1] neg_lo:[1,0,0] neg_hi:[1,0,0]
	v_pk_fma_f32 v[6:7], v[138:139], v[118:119], v[6:7] op_sel_hi:[0,1,1] neg_lo:[1,0,0] neg_hi:[1,0,0]
	v_mov_b32_e32 v17, v22
	global_load_ushort v165, v[44:45], off
	v_mad_u64_u32 v[44:45], s[0:1], s12, v233, v[44:45]
	v_add_u32_e32 v45, s10, v45
	global_load_ushort v188, v[44:45], off
	v_mad_u64_u32 v[44:45], s[0:1], s12, v233, v[44:45]
	v_add_u32_e32 v45, s10, v45
	global_load_ushort v189, v[44:45], off
	v_mad_u64_u32 v[44:45], s[0:1], s12, v233, v[44:45]
	v_add_u32_e32 v45, s10, v45
	global_load_ushort v190, v[44:45], off
	v_mad_u64_u32 v[44:45], s[0:1], s12, v233, v[44:45]
	v_add_u32_e32 v45, s10, v45
	global_load_ushort v191, v[44:45], off
	v_mad_u64_u32 v[44:45], s[0:1], s12, v233, v[44:45]
	v_add_u32_e32 v45, s10, v45
	global_load_ushort v192, v[44:45], off
	v_mad_u64_u32 v[44:45], s[0:1], s12, v233, v[44:45]
	v_add_u32_e32 v45, s10, v45
	global_load_ushort v193, v[44:45], off
	v_mad_u64_u32 v[44:45], s[0:1], s12, v233, v[44:45]
	v_add_u32_e32 v45, s10, v45
	global_load_ushort v194, v[44:45], off
	v_mad_u64_u32 v[44:45], s[0:1], s12, v233, v[44:45]
	v_add_u32_e32 v45, s10, v45
	global_load_ushort v195, v[44:45], off
	v_mad_u64_u32 v[44:45], s[0:1], s12, v233, v[44:45]
	v_add_u32_e32 v45, s10, v45
	global_load_ushort v200, v[44:45], off
	v_mad_u64_u32 v[44:45], s[0:1], s12, v233, v[44:45]
	v_add_u32_e32 v45, s10, v45
	global_load_ushort v201, v[44:45], off
	v_mad_u64_u32 v[44:45], s[0:1], s12, v233, v[44:45]
	v_add_u32_e32 v45, s10, v45
	global_load_ushort v202, v[44:45], off
	v_mad_u64_u32 v[44:45], s[0:1], s12, v233, v[44:45]
	v_add_u32_e32 v45, s10, v45
	global_load_ushort v203, v[44:45], off
	v_mad_u64_u32 v[44:45], s[0:1], s12, v233, v[44:45]
	v_add_u32_e32 v45, s10, v45
	global_load_ushort v204, v[44:45], off
	v_mad_u64_u32 v[44:45], s[0:1], s12, v233, v[44:45]
	v_add_u32_e32 v45, s10, v45
	global_load_ushort v205, v[44:45], off
	v_mad_u64_u32 v[44:45], s[0:1], s12, v233, v[44:45]
	v_add_u32_e32 v45, s10, v45
	global_load_ushort v206, v[44:45], off
	v_mad_u64_u32 v[44:45], s[0:1], s12, v233, v[44:45]
	v_add_u32_e32 v45, s10, v45
	global_load_ushort v207, v[44:45], off
	v_mad_u64_u32 v[44:45], s[0:1], s12, v233, v[44:45]
	v_add_u32_e32 v45, s10, v45
	global_load_ushort v208, v[44:45], off
	v_mad_u64_u32 v[44:45], s[0:1], s12, v233, v[44:45]
	v_add_u32_e32 v45, s10, v45
	s_movk_i32 s0, 0x90
	global_load_ushort v209, v[44:45], off
	s_waitcnt vmcnt(0)
; #define LAS __attribute__((address_space(3)))
; __device__ __forceinline__ float bf2f(unsigned b) { return __uint_as_float(b << 16); }
; __device__ __forceinline__ void solve_diag(float (&x)[64], const LAS float* AT, const int o, const int ja, const int jb) {
; #pragma unroll
;     for (int j = ja; j < jb; ++j) { const float xj = x[o + j];
;         int z = 0; if (j >= 2) asm("" : "+v"(z) : "v"(x[o + j - 2]));
;         const LAS float* ATj = AT + z;
; #pragma unroll
;         for (int i4 = ((j + 1) >> 2) << 2; i4 < 32; i4 += 4) { const f32x4 av = *(const LAS f32x4*)(ATj + j * 36 + i4);
; #pragma unroll
;             for (int t = 0; t < 4; ++t) if (i4 + t > j) x[o + i4 + t] -= av[t] * xj; } }
; __device__ __forceinline__ void phase_gdn_solve(const Args& a, LAS unsigned char* lds, const WCtx& w, int l) {
;     ...
;             { long zz = 0; asm volatile("" : "+v"(zz) : "v"(x[15]));
;               const bf16* xp = PB + (size_t)row0 * NPB + (wv == 0 ? 512 : 256) + h * 64 + lane + zz;
; #pragma unroll
;               for (int i = 32; i < 64; ++i) x[i] = bf2f(xp[sg * i * NPB]); }
;             solve_diag(x, A11T, 0, 16, 31);
	v_lshlrev_b32_e32 v63, 16, v63
	v_lshlrev_b32_e32 v84, 16, v84
	v_lshlrev_b32_e32 v87, 16, v87
	v_lshlrev_b32_e32 v108, 16, v108
	v_lshlrev_b32_e32 v111, 16, v111
	v_lshlrev_b32_e32 v112, 16, v112
	v_lshlrev_b32_e32 v115, 16, v115
	v_lshlrev_b32_e32 v139, 16, v139
	v_lshlrev_b32_e32 v149, 16, v149
	v_lshlrev_b32_e32 v151, 16, v151
	v_lshlrev_b32_e32 v153, 16, v153
	v_lshlrev_b32_e32 v159, 16, v159
	v_lshlrev_b32_e32 v162, 16, v162
	v_lshlrev_b32_e32 v165, 16, v165
	v_lshlrev_b32_e32 v188, 16, v188
	v_lshlrev_b32_e32 v189, 16, v189
	v_lshlrev_b32_e32 v190, 16, v190
	v_lshlrev_b32_e32 v191, 16, v191
	v_lshlrev_b32_e32 v192, 16, v192
	v_lshlrev_b32_e32 v193, 16, v193
	v_lshlrev_b32_e32 v194, 16, v194
	v_lshlrev_b32_e32 v195, 16, v195
	v_lshlrev_b32_e32 v200, 16, v200
	v_lshlrev_b32_e32 v201, 16, v201
	v_lshlrev_b32_e32 v202, 16, v202
	v_lshlrev_b32_e32 v203, 16, v203
	v_lshlrev_b32_e32 v204, 16, v204
	v_lshlrev_b32_e32 v205, 16, v205
	v_lshlrev_b32_e32 v206, 16, v206
	v_lshlrev_b32_e32 v207, 16, v207
	v_lshlrev_b32_e32 v208, 16, v208
	v_lshlrev_b32_e32 v209, 16, v209
	v_mov_b32_e32 v23, v51
	s_nop 0
	v_lshl_add_u32 v23, v23, 2, s27
	ds_read_b128 v[216:219], v23 offset:11584
	ds_read_b128 v[132:135], v23 offset:11600
	ds_read_b128 v[128:131], v23 offset:11616
	ds_read_b128 v[220:223], v23 offset:11632
	s_waitcnt lgkmcnt(3)
	v_fma_f32 v60, -v92, v217, v93
	v_pk_fma_f32 v[6:7], v[92:93], v[218:219], v[6:7] op_sel_hi:[0,1,1] neg_lo:[1,0,0] neg_hi:[1,0,0]
	s_waitcnt lgkmcnt(0)
	v_mov_b32_e32 v4, v221
	v_mov_b32_e32 v5, v222
	v_pk_fma_f32 v[30:31], v[92:93], v[4:5], v[2:3] op_sel_hi:[0,1,1] neg_lo:[1,0,0] neg_hi:[1,0,0]
	v_mov_b32_e32 v2, v51
	v_mov_b32_e32 v56, v223
	v_lshl_add_u32 v2, v2, 2, s27
	ds_read_b64 v[14:15], v2 offset:11736
	ds_read_b128 v[122:125], v2 offset:11744
	ds_read_b128 v[38:41], v2 offset:11760
	ds_read_b128 v[8:11], v2 offset:11776
	v_mov_b32_e32 v2, v51
	v_mov_b32_e32 v57, v220
	v_lshl_add_u32 v2, v2, 2, s27
	ds_read_b128 v[76:79], v2 offset:11872
	ds_read_b128 v[220:223], v2 offset:11888
	ds_read_b128 v[44:47], v2 offset:11904
	ds_read_b128 v[2:5], v2 offset:11920
	s_waitcnt lgkmcnt(3)
	v_pk_fma_f32 v[76:77], v[60:61], v[14:15], v[6:7] op_sel_hi:[0,1,1] neg_lo:[1,0,0] neg_hi:[1,0,0]
	v_mov_b32_e32 v6, v51
	v_mov_b32_e32 v34, v9
	v_lshl_add_u32 v6, v6, 2, s27
	ds_read_b128 v[100:103], v6 offset:12032
	ds_read_b128 v[104:107], v6 offset:12048
	ds_read_b128 v[12:15], v6 offset:12064
	v_mov_b32_e32 v6, v51
	v_fma_f32 v120, -v76, v79, v77
	v_lshl_add_u32 v9, v6, 2, s27
	v_pk_fma_f32 v[6:7], v[170:171], v[184:185], v[178:179] op_sel_hi:[0,1,1] neg_lo:[1,0,0] neg_hi:[1,0,0]
	v_pk_fma_f32 v[6:7], v[148:149], v[16:17], v[6:7] op_sel_hi:[0,1,1] neg_lo:[1,0,0] neg_hi:[1,0,0]
	v_mov_b32_e32 v16, v21
	v_mov_b32_e32 v17, v18
	v_pk_fma_f32 v[6:7], v[172:173], v[16:17], v[6:7] op_sel_hi:[0,1,1] neg_lo:[1,0,0] neg_hi:[1,0,0]
	v_mov_b32_e32 v16, v29
	v_mov_b32_e32 v17, v26
	v_pk_fma_f32 v[6:7], v[150:151], v[16:17], v[6:7] op_sel_hi:[0,1,1] neg_lo:[1,0,0] neg_hi:[1,0,0]
	v_mov_b32_e32 v16, v71
	v_mov_b32_e32 v17, v68
	v_pk_fma_f32 v[6:7], v[140:141], v[16:17], v[6:7] op_sel:[1,0,0] neg_lo:[1,0,0] neg_hi:[1,0,0]
	v_mov_b32_e32 v16, v83
	v_mov_b32_e32 v17, v80
	v_pk_fma_f32 v[6:7], v[136:137], v[16:17], v[6:7] op_sel_hi:[0,1,1] neg_lo:[1,0,0] neg_hi:[1,0,0]
	v_mov_b32_e32 v16, v91
	v_mov_b32_e32 v17, v88
	v_pk_fma_f32 v[6:7], v[142:143], v[16:17], v[6:7] op_sel_hi:[0,1,1] neg_lo:[1,0,0] neg_hi:[1,0,0]
	v_mov_b32_e32 v16, v99
	v_mov_b32_e32 v17, v96
	v_pk_fma_f32 v[6:7], v[138:139], v[16:17], v[6:7] op_sel_hi:[0,1,1] neg_lo:[1,0,0] neg_hi:[1,0,0]
	v_mov_b32_e32 v16, v135
	v_mov_b32_e32 v17, v132
	v_pk_fma_f32 v[6:7], v[92:93], v[16:17], v[6:7] op_sel_hi:[0,1,1] neg_lo:[1,0,0] neg_hi:[1,0,0]
	v_mov_b32_e32 v16, v125
	v_mov_b32_e32 v17, v122
	v_pk_fma_f32 v[6:7], v[60:61], v[16:17], v[6:7] op_sel_hi:[0,1,1] neg_lo:[1,0,0] neg_hi:[1,0,0]
	s_waitcnt lgkmcnt(5)
	v_mov_b32_e32 v16, v223
	v_mov_b32_e32 v17, v220
	v_pk_fma_f32 v[6:7], v[76:77], v[16:17], v[6:7] op_sel_hi:[0,1,1] neg_lo:[1,0,0] neg_hi:[1,0,0]
	s_waitcnt lgkmcnt(2)
	v_mov_b32_e32 v16, v103
	v_mov_b32_e32 v17, v100
	v_pk_fma_f32 v[78:79], v[120:121], v[16:17], v[6:7] op_sel_hi:[0,1,1] neg_lo:[1,0,0] neg_hi:[1,0,0]
	v_pk_fma_f32 v[6:7], v[148:149], v[182:183], v[160:161] op_sel_hi:[0,1,1] neg_lo:[1,0,0] neg_hi:[1,0,0]
	v_mov_b32_e32 v16, v19
	v_mov_b32_e32 v17, v20
	v_pk_fma_f32 v[6:7], v[172:173], v[16:17], v[6:7] op_sel_hi:[0,1,1] neg_lo:[1,0,0] neg_hi:[1,0,0]
	v_mov_b32_e32 v16, v27
	v_mov_b32_e32 v17, v28
	v_pk_fma_f32 v[6:7], v[150:151], v[16:17], v[6:7] op_sel_hi:[0,1,1] neg_lo:[1,0,0] neg_hi:[1,0,0]
	v_mov_b32_e32 v16, v69
	v_mov_b32_e32 v17, v70
	v_pk_fma_f32 v[6:7], v[140:141], v[16:17], v[6:7] op_sel:[1,0,0] neg_lo:[1,0,0] neg_hi:[1,0,0]
	v_mov_b32_e32 v16, v81
	v_mov_b32_e32 v17, v82
	v_pk_fma_f32 v[6:7], v[136:137], v[16:17], v[6:7] op_sel_hi:[0,1,1] neg_lo:[1,0,0] neg_hi:[1,0,0]
	v_mov_b32_e32 v16, v89
	v_mov_b32_e32 v17, v90
	v_pk_fma_f32 v[6:7], v[142:143], v[16:17], v[6:7] op_sel_hi:[0,1,1] neg_lo:[1,0,0] neg_hi:[1,0,0]
	v_mov_b32_e32 v16, v97
	v_mov_b32_e32 v17, v98
	v_pk_fma_f32 v[6:7], v[138:139], v[16:17], v[6:7] op_sel_hi:[0,1,1] neg_lo:[1,0,0] neg_hi:[1,0,0]
	v_mov_b32_e32 v16, v133
	v_mov_b32_e32 v17, v134
	v_pk_fma_f32 v[6:7], v[92:93], v[16:17], v[6:7] op_sel_hi:[0,1,1] neg_lo:[1,0,0] neg_hi:[1,0,0]
	v_mov_b32_e32 v16, v123
	v_mov_b32_e32 v17, v124
	v_pk_fma_f32 v[6:7], v[60:61], v[16:17], v[6:7] op_sel_hi:[0,1,1] neg_lo:[1,0,0] neg_hi:[1,0,0]
	v_mov_b32_e32 v16, v221
	v_mov_b32_e32 v17, v222
	v_pk_fma_f32 v[6:7], v[76:77], v[16:17], v[6:7] op_sel_hi:[0,1,1] neg_lo:[1,0,0] neg_hi:[1,0,0]
	v_mov_b32_e32 v16, v101
	v_mov_b32_e32 v17, v102
	v_pk_fma_f32 v[6:7], v[120:121], v[16:17], v[6:7] op_sel_hi:[0,1,1] neg_lo:[1,0,0] neg_hi:[1,0,0]
	ds_read_b128 v[16:19], v9 offset:12176
	ds_read_b128 v[20:23], v9 offset:12192
	ds_read_b128 v[24:27], v9 offset:12208
	v_mov_b32_e32 v35, v10
	v_mov_b32_e32 v10, v11
	s_waitcnt lgkmcnt(2)
; #define LAS __attribute__((address_space(3)))
; __device__ __forceinline__ void solve_diag(float (&x)[64], const LAS float* AT, const int o, const int ja, const int jb) {
; #pragma unroll
;     for (int j = ja; j < jb; ++j) { const float xj = x[o + j];
;         int z = 0; if (j >= 2) asm("" : "+v"(z) : "v"(x[o + j - 2]));
;         const LAS float* ATj = AT + z;
; #pragma unroll
;         for (int i4 = ((j + 1) >> 2) << 2; i4 < 32; i4 += 4) { const f32x4 av = *(const LAS f32x4*)(ATj + j * 36 + i4);
; #pragma unroll
;             for (int t = 0; t < 4; ++t) if (i4 + t > j) x[o + i4 + t] -= av[t] * xj; } }
	v_mov_b32_e32 v16, v17
	v_mov_b32_e32 v17, v18
	v_pk_fma_f32 v[126:127], v[78:79], v[16:17], v[6:7] op_sel:[1,0,0] neg_lo:[1,0,0] neg_hi:[1,0,0]
	v_mov_b32_e32 v6, v51
	v_fma_f32 v7, -v79, v19, v78
	v_lshl_add_u32 v6, v6, 2, s27
	ds_read_b64 v[28:29], v6 offset:12328
	ds_read_b128 v[16:19], v6 offset:12336
	ds_read_b128 v[80:83], v6 offset:12352
	v_mov_b32_e32 v6, v51
	v_mov_b32_e32 v11, v8
	v_lshl_add_u32 v6, v6, 2, s27
	ds_read_b128 v[68:71], v6 offset:12464
	ds_read_b128 v[88:91], v6 offset:12480
	ds_read_b128 v[94:97], v6 offset:12496
	v_mov_b32_e32 v6, v127
	s_waitcnt lgkmcnt(2)
	v_pk_fma_f32 v[68:69], v[126:127], v[28:29], v[6:7] op_sel_hi:[0,1,1] neg_lo:[1,0,0] neg_hi:[1,0,0]
	v_mov_b32_e32 v6, v51
	v_fma_f32 v160, -v68, v71, v69
	v_lshl_add_u32 v6, v6, 2, s27
	ds_read_b128 v[98:101], v6 offset:12624
	ds_read_b128 v[116:119], v6 offset:12640
	v_mov_b32_e32 v6, v51
	v_mov_b32_e32 v8, v5
	v_lshl_add_u32 v6, v6, 2, s27
	ds_read_b128 v[122:125], v6 offset:12768
	ds_read_b128 v[132:135], v6 offset:12784
	v_pk_fma_f32 v[6:7], v[140:141], v[42:43], v[144:145] op_sel:[1,0,0] neg_lo:[1,0,0] neg_hi:[1,0,0]
	v_mov_b32_e32 v5, v14
	v_pk_fma_f32 v[6:7], v[136:137], v[52:53], v[6:7] op_sel_hi:[0,1,1] neg_lo:[1,0,0] neg_hi:[1,0,0]
	v_pk_fma_f32 v[6:7], v[142:143], v[64:65], v[6:7] op_sel_hi:[0,1,1] neg_lo:[1,0,0] neg_hi:[1,0,0]
	v_pk_fma_f32 v[6:7], v[138:139], v[72:73], v[6:7] op_sel_hi:[0,1,1] neg_lo:[1,0,0] neg_hi:[1,0,0]
	v_pk_fma_f32 v[6:7], v[92:93], v[128:129], v[6:7] op_sel_hi:[0,1,1] neg_lo:[1,0,0] neg_hi:[1,0,0]
	v_pk_fma_f32 v[6:7], v[60:61], v[38:39], v[6:7] op_sel_hi:[0,1,1] neg_lo:[1,0,0] neg_hi:[1,0,0]
	v_pk_fma_f32 v[6:7], v[76:77], v[44:45], v[6:7] op_sel_hi:[0,1,1] neg_lo:[1,0,0] neg_hi:[1,0,0]
	v_pk_fma_f32 v[6:7], v[120:121], v[104:105], v[6:7] op_sel_hi:[0,1,1] neg_lo:[1,0,0] neg_hi:[1,0,0]
	v_pk_fma_f32 v[6:7], v[78:79], v[20:21], v[6:7] op_sel:[1,0,0] neg_lo:[1,0,0] neg_hi:[1,0,0]
	s_nop 0
	v_pk_fma_f32 v[6:7], v[126:127], v[16:17], v[6:7] op_sel_hi:[0,1,1] neg_lo:[1,0,0] neg_hi:[1,0,0]
	v_pk_fma_f32 v[16:17], v[142:143], v[66:67], v[54:55] op_sel_hi:[0,1,1] neg_lo:[1,0,0] neg_hi:[1,0,0]
	v_pk_fma_f32 v[16:17], v[138:139], v[74:75], v[16:17] op_sel_hi:[0,1,1] neg_lo:[1,0,0] neg_hi:[1,0,0]
	v_pk_fma_f32 v[16:17], v[92:93], v[130:131], v[16:17] op_sel_hi:[0,1,1] neg_lo:[1,0,0] neg_hi:[1,0,0]
	v_pk_fma_f32 v[16:17], v[60:61], v[40:41], v[16:17] op_sel_hi:[0,1,1] neg_lo:[1,0,0] neg_hi:[1,0,0]
	s_waitcnt lgkmcnt(5)
	v_pk_fma_f32 v[6:7], v[68:69], v[88:89], v[6:7] op_sel_hi:[0,1,1] neg_lo:[1,0,0] neg_hi:[1,0,0]
	v_pk_fma_f32 v[16:17], v[76:77], v[46:47], v[16:17] op_sel_hi:[0,1,1] neg_lo:[1,0,0] neg_hi:[1,0,0]
	s_waitcnt lgkmcnt(3)
	v_pk_fma_f32 v[70:71], v[160:161], v[98:99], v[6:7] op_sel_hi:[0,1,1] neg_lo:[1,0,0] neg_hi:[1,0,0]
	v_mov_b32_e32 v6, v51
	v_pk_fma_f32 v[16:17], v[120:121], v[106:107], v[16:17] op_sel_hi:[0,1,1] neg_lo:[1,0,0] neg_hi:[1,0,0]
	v_pk_fma_f32 v[16:17], v[78:79], v[22:23], v[16:17] op_sel:[1,0,0] neg_lo:[1,0,0] neg_hi:[1,0,0]
	v_lshl_add_u32 v9, v6, 2, s27
	ds_read_b64 v[6:7], v9 offset:12920
	ds_read_b128 v[36:39], v9 offset:12928
	v_pk_fma_f32 v[16:17], v[126:127], v[18:19], v[16:17] op_sel_hi:[0,1,1] neg_lo:[1,0,0] neg_hi:[1,0,0]
	v_pk_fma_f32 v[16:17], v[68:69], v[90:91], v[16:17] op_sel_hi:[0,1,1] neg_lo:[1,0,0] neg_hi:[1,0,0]
	v_pk_fma_f32 v[16:17], v[160:161], v[100:101], v[16:17] op_sel_hi:[0,1,1] neg_lo:[1,0,0] neg_hi:[1,0,0]
	s_waitcnt lgkmcnt(3)
	v_fma_f32 v64, -v70, v123, v71
	v_pk_fma_f32 v[16:17], v[70:71], v[124:125], v[16:17] op_sel_hi:[0,1,1] neg_lo:[1,0,0] neg_hi:[1,0,0]
	v_mov_b32_e32 v9, v51
	s_waitcnt lgkmcnt(1)
	v_pk_fma_f32 v[66:67], v[64:65], v[6:7], v[16:17] op_sel_hi:[0,1,1] neg_lo:[1,0,0] neg_hi:[1,0,0]
	v_mov_b32_e32 v6, v51
	s_nop 0
	v_lshl_add_u32 v9, v9, 2, s27
	v_lshl_add_u32 v6, v6, 2, s27
	ds_read_b128 v[42:45], v9 offset:13056
	ds_read_b128 v[102:105], v9 offset:13072
	ds_read_b128 v[16:19], v6 offset:13216
	v_mov_b32_e32 v6, v51
	v_mov_b32_e32 v9, v2
	v_lshl_add_u32 v6, v6, 2, s27
	ds_read_b128 v[20:23], v6 offset:13360
	v_pk_fma_f32 v[6:7], v[92:93], v[56:57], v[146:147] op_sel_hi:[0,1,1] neg_lo:[1,0,0] neg_hi:[1,0,0]
	v_pk_fma_f32 v[6:7], v[60:61], v[10:11], v[6:7] op_sel_hi:[0,1,1] neg_lo:[1,0,0] neg_hi:[1,0,0]
	v_pk_fma_f32 v[6:7], v[76:77], v[8:9], v[6:7] op_sel_hi:[0,1,1] neg_lo:[1,0,0] neg_hi:[1,0,0]
	v_mov_b32_e32 v8, v15
	v_mov_b32_e32 v9, v12
	v_pk_fma_f32 v[6:7], v[120:121], v[8:9], v[6:7] op_sel_hi:[0,1,1] neg_lo:[1,0,0] neg_hi:[1,0,0]
	v_mov_b32_e32 v8, v27
	v_mov_b32_e32 v9, v24
	v_pk_fma_f32 v[6:7], v[78:79], v[8:9], v[6:7] op_sel:[1,0,0] neg_lo:[1,0,0] neg_hi:[1,0,0]
	v_mov_b32_e32 v8, v83
	v_mov_b32_e32 v9, v80
	v_pk_fma_f32 v[6:7], v[126:127], v[8:9], v[6:7] op_sel_hi:[0,1,1] neg_lo:[1,0,0] neg_hi:[1,0,0]
	v_mov_b32_e32 v8, v97
	v_mov_b32_e32 v9, v94
	v_pk_fma_f32 v[6:7], v[68:69], v[8:9], v[6:7] op_sel_hi:[0,1,1] neg_lo:[1,0,0] neg_hi:[1,0,0]
	v_mov_b32_e32 v8, v119
	v_mov_b32_e32 v9, v116
	v_pk_fma_f32 v[6:7], v[160:161], v[8:9], v[6:7] op_sel_hi:[0,1,1] neg_lo:[1,0,0] neg_hi:[1,0,0]
	v_mov_b32_e32 v8, v135
	v_mov_b32_e32 v9, v132
	v_pk_fma_f32 v[6:7], v[70:71], v[8:9], v[6:7] op_sel_hi:[0,1,1] neg_lo:[1,0,0] neg_hi:[1,0,0]
	s_waitcnt lgkmcnt(4)
	v_mov_b32_e32 v8, v39
	v_mov_b32_e32 v9, v36
	v_pk_fma_f32 v[6:7], v[64:65], v[8:9], v[6:7] op_sel_hi:[0,1,1] neg_lo:[1,0,0] neg_hi:[1,0,0]
	s_waitcnt lgkmcnt(2)
	v_mov_b32_e32 v8, v105
	v_mov_b32_e32 v9, v102
	v_fma_f32 v62, -v66, v45, v67
	v_pk_fma_f32 v[6:7], v[66:67], v[8:9], v[6:7] op_sel_hi:[0,1,1] neg_lo:[1,0,0] neg_hi:[1,0,0]
	s_waitcnt lgkmcnt(1)
; #define LAS __attribute__((address_space(3)))
; __device__ __forceinline__ unsigned cvt_pk_bf16(float lo, float hi) { unsigned r; asm volatile("v_cvt_pk_bf16_f32 %0, %1, %2" : "=v"(r) : "v"(lo), "v"(hi)); return r; }
; __device__ __forceinline__ void phase_gdn_solve(const Args& a, LAS unsigned char* lds, const WCtx& w, int l) {
;     ...
;             solve_diag(x, A11T, 0, 16, 31);
; #pragma unroll
;             for (int i = 32; i < 64; i += 4) { const f32x4 sc = *(const LAS f32x4*)(BETA + 64 * wv + i);
; #pragma unroll
;                 for (int t = 0; t < 4; ++t) x[i + t] *= sc[t]; }
; #pragma unroll
;             for (int q = 0; q < 4; ++q) { v4u o; o.x = cvt_pk_bf16(x[8 * q], x[8 * q + 1]); o.y = cvt_pk_bf16(x[8 * q + 2], x[8 * q + 3]); o.z = cvt_pk_bf16(x[8 * q + 4], x[8 * q + 5]); o.w = cvt_pk_bf16(x[8 * q + 6], x[8 * q + 7]); *(LAS v4u*)(XT + lane * TS + 8 * q) = o; }
;             f32x16 d0 = zero16(), d1 = zero16();
; #pragma unroll
;             for (int ks = 0; ks < 2; ++ks) { const bf16x8 av = *(const LAS bf16x8*)(A21 + r * TS + 8 * hh + 16 * ks);
;                 const bf16x8 b0 = *(const LAS bf16x8*)(XT + r * TS + 8 * hh + 16 * ks), b1 = *(const LAS bf16x8*)(XT + (32 + r) * TS + 8 * hh + 16 * ks);
;                 d0 = __builtin_amdgcn_mfma_f32_32x32x16_bf16(av, b0, d0, 0, 0, 0); d1 = __builtin_amdgcn_mfma_f32_32x32x16_bf16(av, b1, d1, 0, 0, 0); }
; #pragma unroll
;             for (int e = 0; e < 16; ++e) { const auto sw = __builtin_amdgcn_permlane32_swap(__float_as_uint(d0[e]), __float_as_uint(d1[e]), false, false);
;                 x[32 + 8 * (e >> 2) + (e & 3)] -= __uint_as_float(sw[0]); x[32 + 8 * (e >> 2) + 4 + (e & 3)] -= __uint_as_float(sw[1]); }
;             solve_diag(x, A22T, 32, 0, 31);
	v_mov_b32_e32 v8, v19
	v_mov_b32_e32 v9, v16
	v_pk_fma_f32 v[72:73], v[62:63], v[8:9], v[6:7] op_sel_hi:[0,1,1] neg_lo:[1,0,0] neg_hi:[1,0,0]
	v_pk_fma_f32 v[6:7], v[60:61], v[34:35], v[30:31] op_sel_hi:[0,1,1] neg_lo:[1,0,0] neg_hi:[1,0,0]
	v_mov_b32_e32 v2, v3
	v_mov_b32_e32 v3, v4
	v_pk_fma_f32 v[2:3], v[76:77], v[2:3], v[6:7] op_sel_hi:[0,1,1] neg_lo:[1,0,0] neg_hi:[1,0,0]
	v_mov_b32_e32 v4, v13
	v_pk_fma_f32 v[2:3], v[120:121], v[4:5], v[2:3] op_sel_hi:[0,1,1] neg_lo:[1,0,0] neg_hi:[1,0,0]
	v_mov_b32_e32 v4, v25
	v_mov_b32_e32 v5, v26
	v_pk_fma_f32 v[2:3], v[78:79], v[4:5], v[2:3] op_sel:[1,0,0] neg_lo:[1,0,0] neg_hi:[1,0,0]
	v_mov_b32_e32 v4, v81
	v_mov_b32_e32 v5, v82
	v_pk_fma_f32 v[2:3], v[126:127], v[4:5], v[2:3] op_sel_hi:[0,1,1] neg_lo:[1,0,0] neg_hi:[1,0,0]
	v_mov_b32_e32 v4, v95
	v_mov_b32_e32 v5, v96
	v_pk_fma_f32 v[2:3], v[68:69], v[4:5], v[2:3] op_sel_hi:[0,1,1] neg_lo:[1,0,0] neg_hi:[1,0,0]
	v_mov_b32_e32 v4, v117
	v_mov_b32_e32 v5, v118
	v_pk_fma_f32 v[2:3], v[160:161], v[4:5], v[2:3] op_sel_hi:[0,1,1] neg_lo:[1,0,0] neg_hi:[1,0,0]
	v_mov_b32_e32 v4, v133
	v_mov_b32_e32 v5, v134
	v_pk_fma_f32 v[2:3], v[70:71], v[4:5], v[2:3] op_sel_hi:[0,1,1] neg_lo:[1,0,0] neg_hi:[1,0,0]
	v_mov_b32_e32 v4, v37
	v_mov_b32_e32 v5, v38
	v_pk_fma_f32 v[2:3], v[64:65], v[4:5], v[2:3] op_sel_hi:[0,1,1] neg_lo:[1,0,0] neg_hi:[1,0,0]
	v_mov_b32_e32 v4, v103
	v_mov_b32_e32 v5, v104
	v_pk_fma_f32 v[2:3], v[66:67], v[4:5], v[2:3] op_sel_hi:[0,1,1] neg_lo:[1,0,0] neg_hi:[1,0,0]
	v_mov_b32_e32 v4, v17
	v_mov_b32_e32 v5, v18
	v_pk_fma_f32 v[2:3], v[62:63], v[4:5], v[2:3] op_sel_hi:[0,1,1] neg_lo:[1,0,0] neg_hi:[1,0,0]
	s_waitcnt lgkmcnt(0)
	v_mov_b32_e32 v4, v21
	v_mov_b32_e32 v5, v22
	v_pk_fma_f32 v[122:123], v[72:73], v[4:5], v[2:3] op_sel:[1,0,0] neg_lo:[1,0,0] neg_hi:[1,0,0]
	v_mov_b32_e32 v2, v51
	v_fma_f32 v7, -v73, v23, v72
	v_lshl_add_u32 v6, v2, 2, s27
	v_mov_b32_e32 v2, v51
	s_nop 0
	v_lshl_add_u32 v2, v2, 2, s27
	ds_read_b128 v[2:5], v2 offset:13648
	s_waitcnt lgkmcnt(0)
	ds_read_b64 v[2:3], v6 offset:13512
	v_mov_b32_e32 v6, v123
	ds_read_b128 v[80:83], v214 offset:32640
	ds_read_b128 v[88:91], v214 offset:32656
	ds_read_b128 v[52:55], v214 offset:32672
	ds_read_b128 v[56:59], v214 offset:32688
	ds_read_b128 v[42:45], v214 offset:32704
	ds_read_b128 v[46:49], v214 offset:32720
	ds_read_b128 v[34:37], v214 offset:32736
	ds_read_b128 v[38:41], v214 offset:32752
	s_waitcnt lgkmcnt(8)
	v_pk_fma_f32 v[124:125], v[122:123], v[2:3], v[6:7] op_sel_hi:[0,1,1] neg_lo:[1,0,0] neg_hi:[1,0,0]
	v_mov_b32_e32 v2, s28
	v_mad_u32_u24 v6, v197, s0, v2
	v_cvt_pk_bf16_f32 v2, v163, v156
	v_fma_f32 v96, -v124, v5, v125
	v_cvt_pk_bf16_f32 v3, v164, v152
	v_cvt_pk_bf16_f32 v4, v167, v154
	v_cvt_pk_bf16_f32 v5, v168, v158
	ds_write_b128 v6, v[2:5]
	v_cvt_pk_bf16_f32 v2, v170, v148
	v_cvt_pk_bf16_f32 v3, v172, v150
	v_cvt_pk_bf16_f32 v4, v141, v136
	v_cvt_pk_bf16_f32 v5, v142, v138
	ds_write_b128 v6, v[2:5] offset:16
	v_cvt_pk_bf16_f32 v2, v92, v60
	v_cvt_pk_bf16_f32 v3, v76, v120
	v_cvt_pk_bf16_f32 v4, v79, v126
	v_cvt_pk_bf16_f32 v5, v68, v160
	ds_write_b128 v6, v[2:5] offset:32
	v_cvt_pk_bf16_f32 v2, v70, v64
	v_cvt_pk_bf16_f32 v3, v66, v62
	v_cvt_pk_bf16_f32 v4, v73, v122
	v_cvt_pk_bf16_f32 v5, v124, v96
	ds_write_b128 v6, v[2:5] offset:48
	v_mul_u32_u24_e32 v2, 0x48, v213
	v_lshlrev_b32_e32 v2, 1, v2
	v_lshlrev_b32_e32 v3, 4, v199
	v_add3_u32 v4, s27, v2, v3
	v_add3_u32 v61, s28, v2, v3
	ds_read_b128 v[18:21], v61 offset:4608
	ds_read_b128 v[22:25], v4 offset:18432
	ds_read_b128 v[98:101], v4 offset:18464
	ds_read_b128 v[2:5], v61
	ds_read_b128 v[102:105], v61 offset:32
	s_waitcnt lgkmcnt(1)
	v_mfma_f32_32x32x16_bf16 v[2:17], v[22:25], v[2:5], 0
	ds_read_b128 v[116:119], v61 offset:4640
	s_add_i32 s0, s69, s68
	s_ashr_i32 s1, s0, 31
	s_lshl_b64 s[0:1], s[0:1], 13
	v_mfma_f32_32x32x16_bf16 v[18:33], v[22:25], v[18:21], 0
	s_waitcnt lgkmcnt(1)
	v_mfma_f32_32x32x16_bf16 v[2:17], v[98:101], v[102:105], v[2:17]
	s_waitcnt lgkmcnt(0)
	v_mfma_f32_32x32x16_bf16 v[18:33], v[98:101], v[116:119], v[18:33]
	s_nop 11
	v_permlane32_swap_b32_e32 v2, v18
	v_permlane32_swap_b32_e32 v3, v19
	v_permlane32_swap_b32_e32 v4, v20
	v_permlane32_swap_b32_e32 v5, v21
	v_permlane32_swap_b32_e32 v6, v22
	v_permlane32_swap_b32_e32 v7, v23
	v_permlane32_swap_b32_e32 v8, v24
	v_permlane32_swap_b32_e32 v9, v25
	v_permlane32_swap_b32_e32 v10, v26
	v_permlane32_swap_b32_e32 v11, v27
	v_permlane32_swap_b32_e32 v12, v28
	v_permlane32_swap_b32_e32 v13, v29
	v_permlane32_swap_b32_e32 v14, v30
	v_permlane32_swap_b32_e32 v15, v31
	v_permlane32_swap_b32_e32 v16, v32
	v_permlane32_swap_b32_e32 v17, v33
	v_fma_f32 v2, v80, v63, -v2
	v_fma_f32 v61, v88, v111, -v18
	v_fma_f32 v63, v89, v112, -v19
	v_fma_f32 v65, v82, v87, -v4
	v_fma_f32 v67, v83, v108, -v5
	v_fma_f32 v52, v52, v149, -v6
	v_fma_f32 v53, v53, v151, -v7
	v_fma_f32 v54, v54, v153, -v8
	v_fma_f32 v55, v55, v159, -v9
	v_fma_f32 v42, v42, v190, -v10
	v_fma_f32 v43, v43, v191, -v11
	v_fma_f32 v44, v44, v192, -v12
	v_fma_f32 v45, v45, v193, -v13
	v_fma_f32 v34, v34, v202, -v14
	v_fma_f32 v35, v35, v203, -v15
	v_fma_f32 v36, v36, v204, -v16
	v_fma_f32 v37, v37, v205, -v17
	ds_read_b128 v[128:131], v157 offset:13824
	ds_read_b128 v[132:135], v157 offset:13840
	ds_read_b128 v[144:147], v157 offset:13856
	ds_read_b128 v[174:177], v157 offset:13872
	ds_read_b128 v[178:181], v157 offset:13888
	ds_read_b128 v[182:185], v157 offset:13904
	ds_read_b128 v[216:219], v157 offset:13920
	ds_read_b128 v[220:223], v157 offset:13936
	ds_read_b128 v[242:245], v157 offset:13968
	ds_read_b128 v[246:249], v157 offset:13984
	ds_read_b128 v[98:101], v157 offset:14000
	ds_read_b128 v[102:105], v157 offset:14016
	v_fma_f32 v3, v81, v84, -v3
	v_fma_f32 v30, v38, v206, -v30
	v_fma_f32 v31, v39, v207, -v31
	s_waitcnt lgkmcnt(11)
; #define LAS __attribute__((address_space(3)))
; __device__ __forceinline__ void solve_diag(float (&x)[64], const LAS float* AT, const int o, const int ja, const int jb) {
; #pragma unroll
;     for (int j = ja; j < jb; ++j) { const float xj = x[o + j];
;         int z = 0; if (j >= 2) asm("" : "+v"(z) : "v"(x[o + j - 2]));
;         const LAS float* ATj = AT + z;
; #pragma unroll
;         for (int i4 = ((j + 1) >> 2) << 2; i4 < 32; i4 += 4) { const f32x4 av = *(const LAS f32x4*)(ATj + j * 36 + i4);
; #pragma unroll
;             for (int t = 0; t < 4; ++t) if (i4 + t > j) x[o + i4 + t] -= av[t] * xj; } }
	ds_read_b128 v[116:119], v157 offset:14032
	v_fma_f32 v3, -v2, v129, v3
	v_fma_f32 v38, -v2, v130, v65
	v_fma_f32 v39, -v2, v131, v67
	v_fma_f32 v20, v90, v115, -v20
	v_fma_f32 v21, v91, v139, -v21
	v_fma_f32 v22, v56, v162, -v22
	v_fma_f32 v23, v57, v165, -v23
	s_waitcnt lgkmcnt(11)
	ds_read_b128 v[128:131], v157 offset:14048
	v_fma_f32 v10, -v2, v134, v20
	v_fma_f32 v11, -v2, v135, v21
	s_waitcnt lgkmcnt(10)
	v_fma_f32 v16, -v2, v174, v22
	v_fma_f32 v17, -v2, v175, v23
	s_waitcnt lgkmcnt(9)
	v_fma_f32 v20, -v2, v178, v42
	v_fma_f32 v21, -v2, v179, v43
	v_fma_f32 v22, -v2, v180, v44
	v_fma_f32 v23, -v2, v181, v45
	ds_read_b128 v[178:181], v157 offset:14064
	v_fma_f32 v24, v58, v188, -v24
	v_fma_f32 v25, v59, v189, -v25
	v_fma_f32 v26, v46, v194, -v26
	v_fma_f32 v27, v47, v195, -v27
	v_fma_f32 v28, v48, v200, -v28
	v_fma_f32 v29, v49, v201, -v29
	v_fma_f32 v18, -v2, v176, v24
	v_fma_f32 v19, -v2, v177, v25
	s_waitcnt lgkmcnt(9)
	ds_read_b128 v[174:177], v157 offset:14080
	v_fma_f32 v24, -v2, v182, v26
	v_fma_f32 v25, -v2, v183, v27
	v_fma_f32 v26, -v2, v184, v28
	v_fma_f32 v27, -v2, v185, v29
	ds_read_b128 v[182:185], v157 offset:14112
	v_fma_f32 v32, v40, v208, -v32
	v_fma_f32 v33, v41, v209, -v33
	v_fma_f32 v40, -v2, v132, v61
	v_fma_f32 v41, -v2, v133, v63
	s_waitcnt lgkmcnt(10)
	ds_read_b128 v[132:135], v157 offset:14128
	v_fma_f32 v28, -v2, v216, v34
	v_fma_f32 v29, -v2, v217, v35
	v_fma_f32 v34, -v2, v218, v36
	v_fma_f32 v35, -v2, v219, v37
	ds_read_b128 v[216:219], v157 offset:14144
	v_fma_f32 v12, -v2, v144, v52
	v_fma_f32 v13, -v2, v145, v53
	v_fma_f32 v14, -v2, v146, v54
	v_fma_f32 v15, -v2, v147, v55
	s_waitcnt lgkmcnt(11)
	ds_read_b128 v[144:147], v157 offset:14160
	v_fma_f32 v30, -v2, v220, v30
	v_fma_f32 v31, -v2, v221, v31
	v_fma_f32 v32, -v2, v222, v32
	v_fma_f32 v33, -v2, v223, v33
	s_waitcnt lgkmcnt(11)
	ds_read_b128 v[220:223], v157 offset:14176
	v_fma_f32 v4, -v3, v244, v38
	v_fma_f32 v5, -v3, v245, v39
	s_waitcnt lgkmcnt(11)
	ds_read_b128 v[242:245], v157 offset:14192
	v_fma_f32 v36, -v3, v246, v40
	v_fma_f32 v37, -v3, v247, v41
	v_fma_f32 v38, -v3, v248, v10
	v_fma_f32 v39, -v3, v249, v11
	s_waitcnt lgkmcnt(11)
	ds_read_b128 v[246:249], v157 offset:14208
	v_fma_f32 v40, -v3, v98, v12
	v_fma_f32 v41, -v3, v99, v13
	v_fma_f32 v42, -v3, v100, v14
	v_fma_f32 v43, -v3, v101, v15
	s_waitcnt lgkmcnt(11)
	ds_read_b128 v[98:101], v157 offset:14224
	v_fma_f32 v44, -v3, v102, v16
	v_fma_f32 v45, -v3, v103, v17
	v_fma_f32 v46, -v3, v104, v18
	v_fma_f32 v47, -v3, v105, v19
	s_waitcnt lgkmcnt(11)
	ds_read_b128 v[102:105], v157 offset:14272
	v_fma_f32 v48, -v3, v116, v20
	v_fma_f32 v49, -v3, v117, v21
	v_fma_f32 v22, -v3, v118, v22
	v_fma_f32 v23, -v3, v119, v23
	s_waitcnt lgkmcnt(11)
	ds_read_b128 v[116:119], v157 offset:14288
	v_fma_f32 v24, -v3, v128, v24
	v_fma_f32 v25, -v3, v129, v25
	v_fma_f32 v26, -v3, v130, v26
	v_fma_f32 v27, -v3, v131, v27
	s_waitcnt lgkmcnt(11)
	ds_read_b128 v[128:131], v157 offset:14304
	v_fma_f32 v28, -v3, v178, v28
	v_fma_f32 v29, -v3, v179, v29
	v_fma_f32 v34, -v3, v180, v34
	v_fma_f32 v35, -v3, v181, v35
	s_waitcnt lgkmcnt(11)
	ds_read_b128 v[178:181], v157 offset:14320
	v_fma_f32 v30, -v3, v174, v30
	v_mov_b32_e32 v6, v51
	v_fma_f32 v31, -v3, v175, v31
	v_lshl_add_u32 v52, v6, 2, s27
	v_fma_f32 v32, -v3, v176, v32
	v_fma_f32 v33, -v3, v177, v33
	s_waitcnt lgkmcnt(11)
	ds_read_b128 v[174:177], v157 offset:14336
	v_fma_f32 v5, -v4, v185, v5
	s_waitcnt lgkmcnt(11)
	ds_read_b128 v[182:185], v157 offset:14352
	v_fma_f32 v36, -v4, v132, v36
	v_fma_f32 v37, -v4, v133, v37
	v_fma_f32 v38, -v4, v134, v38
	v_fma_f32 v39, -v4, v135, v39
	s_waitcnt lgkmcnt(9)
	ds_read_b128 v[132:135], v157 offset:14368
	v_fma_f32 v48, -v4, v220, v48
	v_fma_f32 v49, -v4, v221, v49
	v_fma_f32 v22, -v4, v222, v22
	v_fma_f32 v23, -v4, v223, v23
	ds_read_b128 v[220:223], v157 offset:14416
	v_fma_f32 v40, -v4, v216, v40
	v_fma_f32 v41, -v4, v217, v41
	v_fma_f32 v42, -v4, v218, v42
	v_fma_f32 v43, -v4, v219, v43
	s_waitcnt lgkmcnt(10)
	ds_read_b128 v[216:219], v157 offset:14432
	v_fma_f32 v24, -v4, v242, v24
	v_fma_f32 v25, -v4, v243, v25
	v_fma_f32 v26, -v4, v244, v26
	v_fma_f32 v27, -v4, v245, v27
	ds_read_b128 v[242:245], v157 offset:14448
	v_fma_f32 v44, -v4, v144, v44
	v_fma_f32 v45, -v4, v145, v45
	v_fma_f32 v46, -v4, v146, v46
	v_fma_f32 v47, -v4, v147, v47
	s_waitcnt lgkmcnt(11)
	ds_read_b128 v[144:147], v157 offset:14464
	v_fma_f32 v28, -v4, v246, v28
	v_fma_f32 v29, -v4, v247, v29
	v_fma_f32 v34, -v4, v248, v34
	v_fma_f32 v35, -v4, v249, v35
	s_waitcnt lgkmcnt(11)
	ds_read_b128 v[246:249], v157 offset:14480
	v_fma_f32 v30, -v4, v98, v30
	v_mov_b32_e32 v6, v51
	v_fma_f32 v31, -v4, v99, v31
	v_lshl_add_u32 v52, v6, 2, s27
	v_fma_f32 v32, -v4, v100, v32
	v_fma_f32 v33, -v4, v101, v33
	s_waitcnt lgkmcnt(11)
	ds_read_b128 v[98:101], v157 offset:14496
	v_fma_f32 v6, -v5, v102, v36
	v_fma_f32 v7, -v5, v103, v37
	v_fma_f32 v36, -v5, v104, v38
	v_fma_f32 v37, -v5, v105, v39
	s_waitcnt lgkmcnt(11)
	ds_read_b128 v[102:105], v157 offset:14512
	v_fma_f32 v38, -v5, v116, v40
	v_fma_f32 v39, -v5, v117, v41
	v_fma_f32 v40, -v5, v118, v42
	v_fma_f32 v41, -v5, v119, v43
	s_waitcnt lgkmcnt(11)
	ds_read_b128 v[116:119], v157 offset:14560
	v_fma_f32 v42, -v5, v128, v44
	v_fma_f32 v43, -v5, v129, v45
	s_waitcnt lgkmcnt(10)
	v_fma_f32 v24, -v5, v174, v24
	v_fma_f32 v25, -v5, v175, v25
	v_fma_f32 v26, -v5, v176, v26
	v_fma_f32 v27, -v5, v177, v27
	ds_read_b128 v[174:177], v157 offset:14576
	v_fma_f32 v44, -v5, v130, v46
	v_fma_f32 v45, -v5, v131, v47
	v_fma_f32 v46, -v5, v178, v48
	ds_read_b128 v[128:131], v157 offset:14592
	v_fma_f32 v47, -v5, v179, v49
	s_waitcnt lgkmcnt(11)
; #define LAS __attribute__((address_space(3)))
; __device__ __forceinline__ void solve_diag(float (&x)[64], const LAS float* AT, const int o, const int ja, const int jb) {
; #pragma unroll
;     for (int j = ja; j < jb; ++j) { const float xj = x[o + j];
;         int z = 0; if (j >= 2) asm("" : "+v"(z) : "v"(x[o + j - 2]));
;         const LAS float* ATj = AT + z;
; #pragma unroll
;         for (int i4 = ((j + 1) >> 2) << 2; i4 < 32; i4 += 4) { const f32x4 av = *(const LAS f32x4*)(ATj + j * 36 + i4);
; #pragma unroll
;             for (int t = 0; t < 4; ++t) if (i4 + t > j) x[o + i4 + t] -= av[t] * xj; } }
	v_fma_f32 v28, -v5, v182, v28
	v_fma_f32 v29, -v5, v183, v29
	v_fma_f32 v34, -v5, v184, v34
	v_fma_f32 v35, -v5, v185, v35
	ds_read_b128 v[182:185], v157 offset:14608
	v_fma_f32 v48, -v5, v180, v22
	v_fma_f32 v49, -v5, v181, v23
	s_waitcnt lgkmcnt(11)
	ds_read_b128 v[178:181], v157 offset:14624
	v_fma_f32 v30, -v5, v132, v30
	v_mov_b32_e32 v8, v51
	v_fma_f32 v31, -v5, v133, v31
	v_lshl_add_u32 v52, v8, 2, s27
	v_fma_f32 v32, -v5, v134, v32
	v_fma_f32 v33, -v5, v135, v33
	s_waitcnt lgkmcnt(11)
	ds_read_b128 v[132:135], v157 offset:14640
	v_fma_f32 v7, -v6, v221, v7
	v_fma_f32 v36, -v6, v222, v36
	v_fma_f32 v37, -v6, v223, v37
	s_waitcnt lgkmcnt(11)
	ds_read_b128 v[220:223], v157 offset:14656
	v_fma_f32 v38, -v6, v216, v38
	v_fma_f32 v39, -v6, v217, v39
	v_fma_f32 v40, -v6, v218, v40
	v_fma_f32 v41, -v6, v219, v41
	s_waitcnt lgkmcnt(9)
	ds_read_b128 v[216:219], v157 offset:14704
	v_fma_f32 v24, -v6, v246, v24
	v_fma_f32 v25, -v6, v247, v25
	v_fma_f32 v26, -v6, v248, v26
	v_fma_f32 v27, -v6, v249, v27
	ds_read_b128 v[246:249], v157 offset:14720
	v_fma_f32 v42, -v6, v242, v42
	v_fma_f32 v43, -v6, v243, v43
	v_fma_f32 v44, -v6, v244, v44
	v_fma_f32 v45, -v6, v245, v45
	s_waitcnt lgkmcnt(10)
	ds_read_b128 v[242:245], v157 offset:14736
	v_fma_f32 v28, -v6, v98, v28
	v_fma_f32 v29, -v6, v99, v29
	v_fma_f32 v34, -v6, v100, v34
	v_fma_f32 v35, -v6, v101, v35
	ds_read_b128 v[98:101], v157 offset:14752
	v_fma_f32 v46, -v6, v144, v46
	v_fma_f32 v47, -v6, v145, v47
	v_fma_f32 v48, -v6, v146, v48
	v_fma_f32 v49, -v6, v147, v49
	s_waitcnt lgkmcnt(11)
	ds_read_b128 v[144:147], v157 offset:14768
	v_fma_f32 v30, -v6, v102, v30
	v_mov_b32_e32 v8, v51
	v_fma_f32 v31, -v6, v103, v31
	v_lshl_add_u32 v52, v8, 2, s27
	v_fma_f32 v32, -v6, v104, v32
	v_fma_f32 v33, -v6, v105, v33
	s_waitcnt lgkmcnt(11)
	ds_read_b128 v[102:105], v157 offset:14784
	v_fma_f32 v8, -v7, v118, v36
	v_fma_f32 v9, -v7, v119, v37
	s_waitcnt lgkmcnt(11)
	ds_read_b128 v[116:119], v157 offset:14800
	v_fma_f32 v36, -v7, v174, v38
	v_fma_f32 v37, -v7, v175, v39
	v_fma_f32 v38, -v7, v176, v40
	v_fma_f32 v39, -v7, v177, v41
	s_waitcnt lgkmcnt(11)
	ds_read_b128 v[174:177], v157 offset:14864
	v_fma_f32 v40, -v7, v128, v42
	v_fma_f32 v41, -v7, v129, v43
	v_fma_f32 v42, -v7, v130, v44
	v_fma_f32 v43, -v7, v131, v45
	s_waitcnt lgkmcnt(11)
	ds_read_b128 v[128:131], v157 offset:14880
	v_fma_f32 v44, -v7, v182, v46
	v_fma_f32 v45, -v7, v183, v47
	v_fma_f32 v46, -v7, v184, v48
	v_fma_f32 v47, -v7, v185, v49
	s_waitcnt lgkmcnt(11)
	ds_read_b128 v[182:185], v157 offset:14896
	v_fma_f32 v48, -v7, v178, v24
	v_fma_f32 v49, -v7, v179, v25
	v_fma_f32 v26, -v7, v180, v26
	v_fma_f32 v27, -v7, v181, v27
	s_waitcnt lgkmcnt(11)
	ds_read_b128 v[178:181], v157 offset:14912
	v_fma_f32 v28, -v7, v132, v28
	v_fma_f32 v29, -v7, v133, v29
	v_fma_f32 v34, -v7, v134, v34
	v_fma_f32 v35, -v7, v135, v35
	s_waitcnt lgkmcnt(11)
	ds_read_b128 v[132:135], v157 offset:14928
	v_fma_f32 v30, -v7, v220, v30
	v_mov_b32_e32 v10, v51
	v_fma_f32 v31, -v7, v221, v31
	v_lshl_add_u32 v52, v10, 2, s27
	v_fma_f32 v32, -v7, v222, v32
	v_fma_f32 v33, -v7, v223, v33
	s_waitcnt lgkmcnt(11)
	ds_read_b128 v[220:223], v157 offset:14944
	v_fma_f32 v9, -v8, v219, v9
	s_waitcnt lgkmcnt(11)
	ds_read_b128 v[216:219], v157 offset:15008
	v_fma_f32 v36, -v8, v246, v36
	v_fma_f32 v37, -v8, v247, v37
	v_fma_f32 v38, -v8, v248, v38
	v_fma_f32 v39, -v8, v249, v39
	s_waitcnt lgkmcnt(9)
	ds_read_b128 v[246:249], v157 offset:15024
	v_fma_f32 v48, -v8, v144, v48
	v_fma_f32 v49, -v8, v145, v49
	v_fma_f32 v26, -v8, v146, v26
	v_fma_f32 v27, -v8, v147, v27
	ds_read_b128 v[144:147], v157 offset:15040
	v_fma_f32 v40, -v8, v242, v40
	v_fma_f32 v41, -v8, v243, v41
	v_fma_f32 v42, -v8, v244, v42
	v_fma_f32 v43, -v8, v245, v43
	s_waitcnt lgkmcnt(10)
	ds_read_b128 v[242:245], v157 offset:15056
	v_fma_f32 v28, -v8, v102, v28
	v_fma_f32 v29, -v8, v103, v29
	v_fma_f32 v34, -v8, v104, v34
	v_fma_f32 v35, -v8, v105, v35
	ds_read_b128 v[102:105], v157 offset:15072
	v_fma_f32 v44, -v8, v98, v44
	v_fma_f32 v45, -v8, v99, v45
	v_fma_f32 v46, -v8, v100, v46
	v_fma_f32 v47, -v8, v101, v47
	s_waitcnt lgkmcnt(11)
	ds_read_b128 v[98:101], v157 offset:15088
	v_fma_f32 v30, -v8, v116, v30
	v_mov_b32_e32 v10, v51
	v_fma_f32 v31, -v8, v117, v31
	v_lshl_add_u32 v52, v10, 2, s27
	v_fma_f32 v32, -v8, v118, v32
	v_fma_f32 v33, -v8, v119, v33
	s_waitcnt lgkmcnt(11)
	ds_read_b128 v[116:119], v157 offset:15152
	v_fma_f32 v10, -v9, v174, v36
	v_fma_f32 v11, -v9, v175, v37
	v_fma_f32 v36, -v9, v176, v38
	v_fma_f32 v37, -v9, v177, v39
	s_waitcnt lgkmcnt(11)
	ds_read_b128 v[174:177], v157 offset:15168
	v_fma_f32 v38, -v9, v128, v40
	v_fma_f32 v39, -v9, v129, v41
	v_fma_f32 v40, -v9, v130, v42
	v_fma_f32 v41, -v9, v131, v43
	s_waitcnt lgkmcnt(11)
	ds_read_b128 v[128:131], v157 offset:15184
	v_fma_f32 v42, -v9, v182, v44
	v_fma_f32 v43, -v9, v183, v45
	s_waitcnt lgkmcnt(10)
	v_fma_f32 v28, -v9, v132, v28
	v_fma_f32 v29, -v9, v133, v29
	v_fma_f32 v34, -v9, v134, v34
	v_fma_f32 v35, -v9, v135, v35
	ds_read_b128 v[132:135], v157 offset:15200
	v_fma_f32 v44, -v9, v184, v46
	v_fma_f32 v45, -v9, v185, v47
	v_fma_f32 v46, -v9, v178, v48
	ds_read_b128 v[182:185], v157 offset:15216
	v_fma_f32 v47, -v9, v179, v49
	s_waitcnt lgkmcnt(11)
	v_fma_f32 v30, -v9, v220, v30
	v_mov_b32_e32 v12, v51
	v_fma_f32 v48, -v9, v180, v26
	v_lshl_add_u32 v52, v12, 2, s27
	v_fma_f32 v49, -v9, v181, v27
	v_fma_f32 v31, -v9, v221, v31
	ds_read_b128 v[178:181], v157 offset:15232
	v_fma_f32 v32, -v9, v222, v32
	v_fma_f32 v33, -v9, v223, v33
	s_waitcnt lgkmcnt(11)
; #define LAS __attribute__((address_space(3)))
; __device__ __forceinline__ void solve_diag(float (&x)[64], const LAS float* AT, const int o, const int ja, const int jb) {
; #pragma unroll
;     for (int j = ja; j < jb; ++j) { const float xj = x[o + j];
;         int z = 0; if (j >= 2) asm("" : "+v"(z) : "v"(x[o + j - 2]));
;         const LAS float* ATj = AT + z;
; #pragma unroll
;         for (int i4 = ((j + 1) >> 2) << 2; i4 < 32; i4 += 4) { const f32x4 av = *(const LAS f32x4*)(ATj + j * 36 + i4);
; #pragma unroll
;             for (int t = 0; t < 4; ++t) if (i4 + t > j) x[o + i4 + t] -= av[t] * xj; } }
	ds_read_b128 v[220:223], v157 offset:15296
	v_fma_f32 v11, -v10, v217, v11
	v_fma_f32 v36, -v10, v218, v36
	v_fma_f32 v37, -v10, v219, v37
	s_waitcnt lgkmcnt(11)
	ds_read_b128 v[216:219], v157 offset:15312
	v_fma_f32 v38, -v10, v246, v38
	v_fma_f32 v39, -v10, v247, v39
	v_fma_f32 v40, -v10, v248, v40
	v_fma_f32 v41, -v10, v249, v41
	s_waitcnt lgkmcnt(9)
	ds_read_b128 v[246:249], v157 offset:15328
	v_fma_f32 v28, -v10, v102, v28
	v_fma_f32 v29, -v10, v103, v29
	v_fma_f32 v34, -v10, v104, v34
	v_fma_f32 v35, -v10, v105, v35
	ds_read_b128 v[102:105], v157 offset:15344
	v_fma_f32 v42, -v10, v144, v42
	v_fma_f32 v43, -v10, v145, v43
	v_fma_f32 v44, -v10, v146, v44
	v_fma_f32 v45, -v10, v147, v45
	s_waitcnt lgkmcnt(10)
	ds_read_b128 v[144:147], v157 offset:15360
	v_fma_f32 v30, -v10, v98, v30
	v_mov_b32_e32 v12, v51
	v_fma_f32 v46, -v10, v242, v46
	v_lshl_add_u32 v52, v12, 2, s27
	v_fma_f32 v47, -v10, v243, v47
	v_fma_f32 v48, -v10, v244, v48
	v_fma_f32 v49, -v10, v245, v49
	v_fma_f32 v31, -v10, v99, v31
	ds_read_b128 v[242:245], v157 offset:15376
	v_fma_f32 v32, -v10, v100, v32
	v_fma_f32 v33, -v10, v101, v33
	s_waitcnt lgkmcnt(11)
	ds_read_b128 v[98:101], v157 offset:15456
	v_fma_f32 v12, -v11, v118, v36
	v_fma_f32 v13, -v11, v119, v37
	s_waitcnt lgkmcnt(11)
	ds_read_b128 v[116:119], v157 offset:15472
	v_fma_f32 v36, -v11, v174, v38
	v_fma_f32 v37, -v11, v175, v39
	v_fma_f32 v38, -v11, v176, v40
	v_fma_f32 v39, -v11, v177, v41
	s_waitcnt lgkmcnt(11)
	ds_read_b128 v[174:177], v157 offset:15488
	v_fma_f32 v40, -v11, v128, v42
	v_fma_f32 v41, -v11, v129, v43
	v_fma_f32 v42, -v11, v130, v44
	v_fma_f32 v43, -v11, v131, v45
	s_waitcnt lgkmcnt(11)
	ds_read_b128 v[128:131], v157 offset:15504
	v_fma_f32 v44, -v11, v132, v46
	v_fma_f32 v45, -v11, v133, v47
	v_fma_f32 v46, -v11, v134, v48
	v_fma_f32 v47, -v11, v135, v49
	s_waitcnt lgkmcnt(11)
	ds_read_b128 v[132:135], v157 offset:15520
	v_fma_f32 v48, -v11, v182, v28
	v_fma_f32 v49, -v11, v183, v29
	v_fma_f32 v34, -v11, v184, v34
	v_fma_f32 v35, -v11, v185, v35
	s_waitcnt lgkmcnt(11)
	ds_read_b128 v[182:185], v157 offset:15600
	v_fma_f32 v30, -v11, v178, v30
	v_mov_b32_e32 v14, v51
	v_fma_f32 v31, -v11, v179, v31
	v_lshl_add_u32 v52, v14, 2, s27
	v_fma_f32 v32, -v11, v180, v32
	v_fma_f32 v33, -v11, v181, v33
	s_waitcnt lgkmcnt(11)
	ds_read_b128 v[178:181], v157 offset:15616
	v_fma_f32 v13, -v12, v223, v13
	s_waitcnt lgkmcnt(11)
	ds_read_b128 v[220:223], v157 offset:15632
	v_fma_f32 v36, -v12, v216, v36
	v_fma_f32 v37, -v12, v217, v37
	v_fma_f32 v38, -v12, v218, v38
	v_fma_f32 v39, -v12, v219, v39
	s_waitcnt lgkmcnt(9)
	ds_read_b128 v[216:219], v157 offset:15648
	v_fma_f32 v48, -v12, v144, v48
	v_fma_f32 v49, -v12, v145, v49
	v_fma_f32 v34, -v12, v146, v34
	v_fma_f32 v35, -v12, v147, v35
	ds_read_b128 v[144:147], v157 offset:15664
	v_fma_f32 v40, -v12, v246, v40
	v_fma_f32 v41, -v12, v247, v41
	v_fma_f32 v42, -v12, v248, v42
	v_fma_f32 v43, -v12, v249, v43
	s_waitcnt lgkmcnt(10)
	ds_read_b128 v[246:249], v157 offset:15744
	v_fma_f32 v30, -v12, v242, v30
	v_mov_b32_e32 v14, v51
	v_fma_f32 v44, -v12, v102, v44
	v_lshl_add_u32 v52, v14, 2, s27
	v_fma_f32 v45, -v12, v103, v45
	v_fma_f32 v46, -v12, v104, v46
	v_fma_f32 v47, -v12, v105, v47
	v_fma_f32 v31, -v12, v243, v31
	ds_read_b128 v[102:105], v157 offset:15760
	v_fma_f32 v32, -v12, v244, v32
	v_fma_f32 v33, -v12, v245, v33
	s_waitcnt lgkmcnt(11)
	ds_read_b128 v[242:245], v157 offset:15776
	v_fma_f32 v14, -v13, v98, v36
	v_fma_f32 v15, -v13, v99, v37
	v_fma_f32 v36, -v13, v100, v38
	v_fma_f32 v37, -v13, v101, v39
	s_waitcnt lgkmcnt(11)
	ds_read_b128 v[98:101], v157 offset:15792
	v_fma_f32 v38, -v13, v116, v40
	v_fma_f32 v39, -v13, v117, v41
	v_fma_f32 v40, -v13, v118, v42
	s_waitcnt lgkmcnt(11)
	v_fma_f32 v42, -v13, v174, v44
	v_fma_f32 v44, -v13, v176, v46
	s_waitcnt lgkmcnt(10)
	v_fma_f32 v46, -v13, v128, v48
	s_waitcnt lgkmcnt(9)
	v_fma_f32 v48, -v13, v132, v30
	v_mov_b32_e32 v16, v51
	v_fma_f32 v41, -v13, v119, v43
	v_lshl_add_u32 v52, v16, 2, s27
	ds_read_b128 v[116:119], v157 offset:15808
	v_fma_f32 v43, -v13, v175, v45
	v_fma_f32 v45, -v13, v177, v47
	v_fma_f32 v47, -v13, v129, v49
	ds_read_b128 v[174:177], v157 offset:15888
	v_fma_f32 v34, -v13, v130, v34
	v_fma_f32 v35, -v13, v131, v35
	v_fma_f32 v49, -v13, v133, v31
	ds_read_b128 v[128:131], v157 offset:15904
	v_fma_f32 v32, -v13, v134, v32
	v_fma_f32 v33, -v13, v135, v33
	s_waitcnt lgkmcnt(11)
	ds_read_b128 v[132:135], v157 offset:15920
	v_fma_f32 v15, -v14, v183, v15
	v_fma_f32 v36, -v14, v184, v36
	v_fma_f32 v37, -v14, v185, v37
	s_waitcnt lgkmcnt(11)
	ds_read_b128 v[182:185], v157 offset:15936
	v_fma_f32 v38, -v14, v178, v38
	v_fma_f32 v39, -v14, v179, v39
	v_fma_f32 v40, -v14, v180, v40
	v_fma_f32 v41, -v14, v181, v41
	s_waitcnt lgkmcnt(9)
	ds_read_b128 v[178:181], v157 offset:15952
	v_fma_f32 v48, -v14, v144, v48
	v_mov_b32_e32 v16, v51
	v_fma_f32 v42, -v14, v220, v42
	v_lshl_add_u32 v52, v16, 2, s27
	v_fma_f32 v43, -v14, v221, v43
	v_fma_f32 v44, -v14, v222, v44
	v_fma_f32 v45, -v14, v223, v45
	v_fma_f32 v46, -v14, v216, v46
	ds_read_b128 v[220:223], v157 offset:16048
	v_fma_f32 v47, -v14, v217, v47
	v_fma_f32 v34, -v14, v218, v34
	v_fma_f32 v35, -v14, v219, v35
	v_fma_f32 v49, -v14, v145, v49
	ds_read_b128 v[216:219], v157 offset:16064
	v_fma_f32 v32, -v14, v146, v32
	v_fma_f32 v33, -v14, v147, v33
	s_waitcnt lgkmcnt(11)
	ds_read_b128 v[144:147], v157 offset:16080
	v_fma_f32 v16, -v15, v248, v36
	v_fma_f32 v17, -v15, v249, v37
	s_waitcnt lgkmcnt(11)
	ds_read_b128 v[246:249], v157 offset:16096
	v_fma_f32 v36, -v15, v102, v38
	v_fma_f32 v37, -v15, v103, v39
	v_fma_f32 v38, -v15, v104, v40
	s_waitcnt lgkmcnt(11)
; #define LAS __attribute__((address_space(3)))
; __device__ __forceinline__ void solve_diag(float (&x)[64], const LAS float* AT, const int o, const int ja, const int jb) {
; #pragma unroll
;     for (int j = ja; j < jb; ++j) { const float xj = x[o + j];
;         int z = 0; if (j >= 2) asm("" : "+v"(z) : "v"(x[o + j - 2]));
;         const LAS float* ATj = AT + z;
; #pragma unroll
;         for (int i4 = ((j + 1) >> 2) << 2; i4 < 32; i4 += 4) { const f32x4 av = *(const LAS f32x4*)(ATj + j * 36 + i4);
; #pragma unroll
;             for (int t = 0; t < 4; ++t) if (i4 + t > j) x[o + i4 + t] -= av[t] * xj; } }
	v_fma_f32 v40, -v15, v242, v42
	v_fma_f32 v42, -v15, v244, v44
	s_waitcnt lgkmcnt(10)
	v_fma_f32 v44, -v15, v98, v46
	s_waitcnt lgkmcnt(9)
	v_fma_f32 v46, -v15, v116, v48
	v_mov_b32_e32 v18, v51
	v_fma_f32 v39, -v15, v105, v41
	v_lshl_add_u32 v52, v18, 2, s27
	ds_read_b128 v[102:105], v157 offset:16192
	v_fma_f32 v41, -v15, v243, v43
	v_fma_f32 v43, -v15, v245, v45
	v_fma_f32 v45, -v15, v99, v47
	ds_read_b128 v[242:245], v157 offset:16208
	v_fma_f32 v34, -v15, v100, v34
	v_fma_f32 v35, -v15, v101, v35
	v_fma_f32 v47, -v15, v117, v49
	ds_read_b128 v[98:101], v157 offset:16224
	v_fma_f32 v48, -v15, v118, v32
	v_fma_f32 v49, -v15, v119, v33
	s_waitcnt lgkmcnt(11)
	ds_read_b128 v[116:119], v157 offset:16240
	v_fma_f32 v17, -v16, v177, v17
	s_waitcnt lgkmcnt(11)
	ds_read_b128 v[174:177], v157 offset:16336
	v_fma_f32 v24, -v16, v130, v38
	s_waitcnt lgkmcnt(10)
	v_fma_f32 v32, -v16, v184, v34
	v_fma_f32 v22, -v16, v128, v36
	v_fma_f32 v23, -v16, v129, v37
	s_waitcnt lgkmcnt(9)
	v_fma_f32 v34, -v16, v178, v46
	v_mov_b32_e32 v18, v51
	v_fma_f32 v33, -v16, v185, v35
	v_lshl_add_u32 v38, v18, 2, s27
	v_fma_f32 v35, -v16, v179, v47
	v_fma_f32 v36, -v16, v180, v48
	v_fma_f32 v37, -v16, v181, v49
	ds_read_b128 v[178:181], v157 offset:16352
	v_fma_f32 v25, -v16, v131, v39
	v_fma_f32 v26, -v16, v132, v40
	ds_read_b128 v[128:131], v157 offset:16368
	v_fma_f32 v27, -v16, v133, v41
	v_fma_f32 v28, -v16, v134, v42
	s_waitcnt lgkmcnt(10)
	v_fma_f32 v18, -v17, v220, v22
	v_fma_f32 v19, -v17, v221, v23
	v_fma_f32 v24, -v17, v222, v24
	v_fma_f32 v25, -v17, v223, v25
	ds_read_b128 v[220:223], v157 offset:16384
	v_fma_f32 v29, -v16, v135, v43
	v_fma_f32 v30, -v16, v182, v44
	ds_read_b128 v[132:135], v157 offset:16480
	v_fma_f32 v31, -v16, v183, v45
	s_waitcnt lgkmcnt(11)
	ds_read_b128 v[182:185], v157 offset:16496
	v_fma_f32 v26, -v17, v216, v26
	v_fma_f32 v27, -v17, v217, v27
	v_fma_f32 v28, -v17, v218, v28
	v_fma_f32 v29, -v17, v219, v29
	s_waitcnt lgkmcnt(11)
	ds_read_b128 v[216:219], v157 offset:16512
	v_fma_f32 v30, -v17, v144, v30
	v_fma_f32 v31, -v17, v145, v31
	v_fma_f32 v32, -v17, v146, v32
	v_fma_f32 v33, -v17, v147, v33
	s_waitcnt lgkmcnt(11)
	ds_read_b128 v[144:147], v157 offset:16528
	v_fma_f32 v34, -v17, v246, v34
	v_mov_b32_e32 v20, v51
	v_fma_f32 v35, -v17, v247, v35
	v_lshl_add_u32 v38, v20, 2, s27
	v_fma_f32 v36, -v17, v248, v36
	v_fma_f32 v37, -v17, v249, v37
	s_waitcnt lgkmcnt(11)
	ds_read_b128 v[246:249], v157 offset:16640
	v_fma_f32 v19, -v18, v103, v19
	v_fma_f32 v24, -v18, v104, v24
	v_fma_f32 v25, -v18, v105, v25
	s_waitcnt lgkmcnt(11)
	ds_read_b128 v[102:105], v157 offset:16656
	v_fma_f32 v26, -v18, v242, v26
	v_fma_f32 v27, -v18, v243, v27
	v_fma_f32 v28, -v18, v244, v28
	v_fma_f32 v29, -v18, v245, v29
	s_waitcnt lgkmcnt(11)
	ds_read_b128 v[242:245], v157 offset:16672
	v_fma_f32 v30, -v18, v98, v30
	v_fma_f32 v31, -v18, v99, v31
	v_fma_f32 v32, -v18, v100, v32
	v_fma_f32 v33, -v18, v101, v33
	s_waitcnt lgkmcnt(11)
	ds_read_b128 v[98:101], v157 offset:16784
	v_fma_f32 v34, -v18, v116, v34
	v_mov_b32_e32 v20, v51
	v_fma_f32 v35, -v18, v117, v35
	v_lshl_add_u32 v38, v20, 2, s27
	v_fma_f32 v36, -v18, v118, v36
	v_fma_f32 v37, -v18, v119, v37
	s_waitcnt lgkmcnt(11)
	ds_read_b128 v[116:119], v157 offset:16800
	v_fma_f32 v20, -v19, v176, v24
	v_fma_f32 v21, -v19, v177, v25
	s_waitcnt lgkmcnt(11)
	ds_read_b128 v[174:177], v157 offset:16816
	v_fma_f32 v26, -v19, v178, v26
	v_fma_f32 v27, -v19, v179, v27
	v_fma_f32 v28, -v19, v180, v28
	v_fma_f32 v29, -v19, v181, v29
	s_waitcnt lgkmcnt(11)
	ds_read_b128 v[178:181], v157 offset:16928
	v_fma_f32 v30, -v19, v128, v30
	v_fma_f32 v31, -v19, v129, v31
	v_fma_f32 v32, -v19, v130, v32
	v_fma_f32 v33, -v19, v131, v33
	s_waitcnt lgkmcnt(11)
	ds_read_b128 v[128:131], v157 offset:16944
	v_fma_f32 v34, -v19, v220, v34
	v_mov_b32_e32 v22, v51
	v_fma_f32 v35, -v19, v221, v35
	v_lshl_add_u32 v38, v22, 2, s27
	v_fma_f32 v36, -v19, v222, v36
	v_fma_f32 v37, -v19, v223, v37
	s_waitcnt lgkmcnt(11)
	ds_read_b128 v[220:223], v157 offset:16960
	v_fma_f32 v21, -v20, v135, v21
	s_waitcnt lgkmcnt(11)
	ds_read_b128 v[132:135], v157 offset:17072
	v_fma_f32 v26, -v20, v182, v26
	v_fma_f32 v27, -v20, v183, v27
	v_fma_f32 v28, -v20, v184, v28
	v_fma_f32 v29, -v20, v185, v29
	s_waitcnt lgkmcnt(11)
	ds_read_b128 v[182:185], v157 offset:17088
	v_fma_f32 v30, -v20, v216, v30
	v_fma_f32 v31, -v20, v217, v31
	v_fma_f32 v32, -v20, v218, v32
	v_fma_f32 v33, -v20, v219, v33
	s_waitcnt lgkmcnt(11)
	ds_read_b128 v[216:219], v157 offset:17104
	v_fma_f32 v34, -v20, v144, v34
	v_mov_b32_e32 v22, v51
	v_fma_f32 v35, -v20, v145, v35
	v_lshl_add_u32 v38, v22, 2, s27
	v_fma_f32 v36, -v20, v146, v36
	v_fma_f32 v37, -v20, v147, v37
	s_waitcnt lgkmcnt(11)
	ds_read_b128 v[144:147], v157 offset:17232
	v_fma_f32 v22, -v21, v246, v26
	v_fma_f32 v23, -v21, v247, v27
	v_fma_f32 v28, -v21, v248, v28
	v_fma_f32 v29, -v21, v249, v29
	s_waitcnt lgkmcnt(11)
	ds_read_b128 v[246:249], v157 offset:17248
	v_fma_f32 v30, -v21, v102, v30
	v_fma_f32 v31, -v21, v103, v31
	v_fma_f32 v32, -v21, v104, v32
	v_fma_f32 v33, -v21, v105, v33
	s_waitcnt lgkmcnt(11)
	ds_read_b128 v[102:105], v157 offset:17376
	v_fma_f32 v34, -v21, v242, v34
	v_mov_b32_e32 v24, v51
	v_fma_f32 v35, -v21, v243, v35
	v_lshl_add_u32 v38, v24, 2, s27
	v_fma_f32 v36, -v21, v244, v36
	v_fma_f32 v37, -v21, v245, v37
	s_waitcnt lgkmcnt(11)
	ds_read_b128 v[242:245], v157 offset:17392
	v_fma_f32 v23, -v22, v99, v23
	v_fma_f32 v28, -v22, v100, v28
	v_fma_f32 v29, -v22, v101, v29
	s_waitcnt lgkmcnt(11)
	ds_read_b128 v[98:101], v157 offset:17520
	v_fma_f32 v30, -v22, v116, v30
	v_fma_f32 v31, -v22, v117, v31
	v_fma_f32 v32, -v22, v118, v32
	v_fma_f32 v33, -v22, v119, v33
	s_waitcnt lgkmcnt(11)
; #define LAS __attribute__((address_space(3)))
; __device__ __forceinline__ unsigned f2bf(float f) { unsigned u = __float_as_uint(f); return (u + 0x7fffu + ((u >> 16) & 1u)) >> 16; }
; __device__ __forceinline__ unsigned cvt_pk_bf16(float lo, float hi) { unsigned r; asm volatile("v_cvt_pk_bf16_f32 %0, %1, %2" : "=v"(r) : "v"(lo), "v"(hi)); return r; }
; __device__ __forceinline__ void solve_diag(float (&x)[64], const LAS float* AT, const int o, const int ja, const int jb) {
; #pragma unroll
;     for (int j = ja; j < jb; ++j) { const float xj = x[o + j];
;         int z = 0; if (j >= 2) asm("" : "+v"(z) : "v"(x[o + j - 2]));
;         const LAS float* ATj = AT + z;
; #pragma unroll
;         for (int i4 = ((j + 1) >> 2) << 2; i4 < 32; i4 += 4) { const f32x4 av = *(const LAS f32x4*)(ATj + j * 36 + i4);
; #pragma unroll
;             for (int t = 0; t < 4; ++t) if (i4 + t > j) x[o + i4 + t] -= av[t] * xj; } }
; __device__ __forceinline__ void phase_gdn_solve(const Args& a, LAS unsigned char* lds, const WCtx& w, int l) {
;     ...
;             {
;                 if (wv == 0) { bf16* dst = UT + ((size_t)(chain * 36 + c) * 64 + lane) * 64;
; #pragma unroll
;                     for (int q = 0; q < 8; ++q) { v4u o; o.x = cvt_pk_bf16(x[8 * q], x[8 * q + 1]); o.y = cvt_pk_bf16(x[8 * q + 2], x[8 * q + 3]); o.z = cvt_pk_bf16(x[8 * q + 4], x[8 * q + 5]); o.w = cvt_pk_bf16(x[8 * q + 6], x[8 * q + 7]); *(v4u*)(dst + 8 * q) = o; } }
;                 else { bf16* dst = WW + (size_t)(chain * 36 + c) * 4096 + lane;
; #pragma unroll
;                     for (int j = 0; j < 64; ++j) dst[j * 64] = (bf16)f2bf(x[j]); }
	ds_read_b128 v[116:119], v157 offset:17536
	v_fma_f32 v34, -v22, v174, v34
	v_mov_b32_e32 v24, v51
	v_fma_f32 v35, -v22, v175, v35
	v_lshl_add_u32 v38, v24, 2, s27
	v_fma_f32 v36, -v22, v176, v36
	v_fma_f32 v37, -v22, v177, v37
	s_waitcnt lgkmcnt(11)
	ds_read_b128 v[174:177], v157 offset:17664
	v_fma_f32 v24, -v23, v180, v28
	v_fma_f32 v25, -v23, v181, v29
	s_waitcnt lgkmcnt(11)
	ds_read_b128 v[178:181], v157 offset:17680
	v_fma_f32 v30, -v23, v128, v30
	v_fma_f32 v31, -v23, v129, v31
	v_fma_f32 v32, -v23, v130, v32
	v_fma_f32 v33, -v23, v131, v33
	s_waitcnt lgkmcnt(11)
	ds_read_b128 v[128:131], v157 offset:17824
	v_fma_f32 v34, -v23, v220, v34
	v_mov_b32_e32 v26, v51
	v_fma_f32 v35, -v23, v221, v35
	v_lshl_add_u32 v38, v26, 2, s27
	v_fma_f32 v36, -v23, v222, v36
	v_fma_f32 v37, -v23, v223, v37
	s_waitcnt lgkmcnt(11)
	ds_read_b128 v[220:223], v157 offset:17968
	v_fma_f32 v25, -v24, v135, v25
	s_waitcnt lgkmcnt(11)
	ds_read_b128 v[132:135], v157 offset:18112
	v_fma_f32 v30, -v24, v182, v30
	v_fma_f32 v31, -v24, v183, v31
	v_fma_f32 v32, -v24, v184, v32
	v_fma_f32 v33, -v24, v185, v33
	s_waitcnt lgkmcnt(11)
	ds_read_b128 v[182:185], v157 offset:18256
	v_fma_f32 v34, -v24, v216, v34
	v_mov_b32_e32 v26, v51
	v_fma_f32 v35, -v24, v217, v35
	v_lshl_add_u32 v38, v26, 2, s27
	v_fma_f32 v36, -v24, v218, v36
	v_fma_f32 v37, -v24, v219, v37
	s_waitcnt lgkmcnt(11)
	v_fma_f32 v26, -v25, v144, v30
	v_fma_f32 v27, -v25, v145, v31
	v_fma_f32 v32, -v25, v146, v32
	v_fma_f32 v33, -v25, v147, v33
	s_waitcnt lgkmcnt(10)
	v_fma_f32 v34, -v25, v246, v34
	v_mov_b32_e32 v28, v51
	v_fma_f32 v35, -v25, v247, v35
	v_lshl_add_u32 v38, v28, 2, s27
	v_fma_f32 v36, -v25, v248, v36
	v_fma_f32 v37, -v25, v249, v37
	s_waitcnt lgkmcnt(9)
	v_fma_f32 v27, -v26, v103, v27
	v_fma_f32 v32, -v26, v104, v32
	v_fma_f32 v33, -v26, v105, v33
	s_waitcnt lgkmcnt(8)
	v_fma_f32 v34, -v26, v242, v34
	v_mov_b32_e32 v28, v51
	v_fma_f32 v35, -v26, v243, v35
	v_lshl_add_u32 v38, v28, 2, s27
	v_fma_f32 v36, -v26, v244, v36
	v_fma_f32 v37, -v26, v245, v37
	s_waitcnt lgkmcnt(7)
	v_fma_f32 v28, -v27, v100, v32
	v_fma_f32 v29, -v27, v101, v33
	s_waitcnt lgkmcnt(6)
	v_fma_f32 v34, -v27, v116, v34
	v_mov_b32_e32 v30, v51
	v_fma_f32 v35, -v27, v117, v35
	v_lshl_add_u32 v38, v30, 2, s27
	v_fma_f32 v36, -v27, v118, v36
	v_fma_f32 v37, -v27, v119, v37
	s_waitcnt lgkmcnt(5)
	v_fma_f32 v29, -v28, v177, v29
	s_waitcnt lgkmcnt(4)
	v_fma_f32 v34, -v28, v178, v34
	v_mov_b32_e32 v30, v51
	v_fma_f32 v35, -v28, v179, v35
	v_lshl_add_u32 v30, v30, 2, s27
	v_fma_f32 v36, -v28, v180, v36
	v_fma_f32 v37, -v28, v181, v37
	s_waitcnt lgkmcnt(3)
	v_fma_f32 v36, -v29, v130, v36
	v_mov_b32_e32 v32, v51
	v_fma_f32 v30, -v29, v128, v34
	v_lshl_add_u32 v32, v32, 2, s27
	v_fma_f32 v31, -v29, v129, v35
	v_fma_f32 v37, -v29, v131, v37
	s_waitcnt lgkmcnt(2)
	v_mov_b32_e32 v32, v51
	v_fma_f32 v31, -v30, v221, v31
	v_lshl_add_u32 v32, v32, 2, s27
	v_fma_f32 v36, -v30, v222, v36
	v_fma_f32 v37, -v30, v223, v37
	s_waitcnt lgkmcnt(1)
	v_fma_f32 v32, -v31, v134, v36
	v_mov_b32_e32 v34, v51
	v_fma_f32 v33, -v31, v135, v37
	v_lshl_add_u32 v34, v34, 2, s27
	s_waitcnt lgkmcnt(0)
	v_fma_f32 v33, -v32, v185, v33
	v_mov_b32_e32 v34, v182
	v_mov_b32_e32 v35, v183
	v_mov_b32_e32 v36, v184
	v_mov_b32_e32 v37, v185
	s_cbranch_vccz .LBB0_1065
	v_readlane_b32 s2, v253, 57
	v_readlane_b32 s3, v253, 58
	s_add_u32 s2, s2, s0
	v_bfe_u32 v36, v163, 16, 1
	s_movk_i32 s10, 0x7fff
	s_addc_u32 s3, s3, s1
	v_add3_u32 v36, v163, v36, s10
	global_store_short_d16_hi v50, v36, s[2:3]
	v_bfe_u32 v36, v156, 16, 1
	v_add3_u32 v36, v156, v36, s10
	global_store_short_d16_hi v50, v36, s[2:3] offset:128
	v_bfe_u32 v36, v164, 16, 1
	v_add3_u32 v36, v164, v36, s10
	global_store_short_d16_hi v50, v36, s[2:3] offset:256
	v_bfe_u32 v36, v152, 16, 1
	v_add3_u32 v36, v152, v36, s10
	global_store_short_d16_hi v50, v36, s[2:3] offset:384
	v_bfe_u32 v36, v167, 16, 1
	v_add3_u32 v36, v167, v36, s10
	global_store_short_d16_hi v50, v36, s[2:3] offset:512
	v_bfe_u32 v36, v154, 16, 1
	v_add3_u32 v36, v154, v36, s10
	global_store_short_d16_hi v50, v36, s[2:3] offset:640
	v_bfe_u32 v36, v168, 16, 1
	v_add3_u32 v36, v168, v36, s10
	global_store_short_d16_hi v50, v36, s[2:3] offset:768
	v_bfe_u32 v36, v158, 16, 1
	v_add3_u32 v36, v158, v36, s10
	global_store_short_d16_hi v50, v36, s[2:3] offset:896
	v_bfe_u32 v36, v170, 16, 1
	v_add3_u32 v36, v170, v36, s10
	global_store_short_d16_hi v50, v36, s[2:3] offset:1024
	v_bfe_u32 v36, v148, 16, 1
	v_add3_u32 v36, v148, v36, s10
	global_store_short_d16_hi v50, v36, s[2:3] offset:1152
	v_bfe_u32 v36, v172, 16, 1
	v_add3_u32 v36, v172, v36, s10
	global_store_short_d16_hi v50, v36, s[2:3] offset:1280
	v_bfe_u32 v36, v150, 16, 1
	v_add3_u32 v36, v150, v36, s10
	global_store_short_d16_hi v50, v36, s[2:3] offset:1408
	v_bfe_u32 v36, v141, 16, 1
	v_add3_u32 v36, v141, v36, s10
	global_store_short_d16_hi v50, v36, s[2:3] offset:1536
	v_bfe_u32 v36, v136, 16, 1
	v_add3_u32 v36, v136, v36, s10
	global_store_short_d16_hi v50, v36, s[2:3] offset:1664
	v_bfe_u32 v36, v142, 16, 1
	v_add3_u32 v36, v142, v36, s10
	global_store_short_d16_hi v50, v36, s[2:3] offset:1792
	v_bfe_u32 v36, v138, 16, 1
	v_add3_u32 v36, v138, v36, s10
	global_store_short_d16_hi v50, v36, s[2:3] offset:1920
	v_bfe_u32 v36, v92, 16, 1
	v_add3_u32 v36, v92, v36, s10
	global_store_short_d16_hi v50, v36, s[2:3] offset:2048
	v_bfe_u32 v36, v60, 16, 1
	v_add3_u32 v36, v60, v36, s10
	global_store_short_d16_hi v50, v36, s[2:3] offset:2176
	v_bfe_u32 v36, v76, 16, 1
	v_add3_u32 v36, v76, v36, s10
	global_store_short_d16_hi v50, v36, s[2:3] offset:2304
	v_bfe_u32 v36, v120, 16, 1
; __device__ __forceinline__ unsigned f2bf(float f) { unsigned u = __float_as_uint(f); return (u + 0x7fffu + ((u >> 16) & 1u)) >> 16; }
; __device__ __forceinline__ void phase_gdn_solve(const Args& a, LAS unsigned char* lds, const WCtx& w, int l) {
;     ...
;                 else { bf16* dst = WW + (size_t)(chain * 36 + c) * 4096 + lane;
; #pragma unroll
;                     for (int j = 0; j < 64; ++j) dst[j * 64] = (bf16)f2bf(x[j]); }
	v_add3_u32 v36, v120, v36, s10
	global_store_short_d16_hi v50, v36, s[2:3] offset:2432
	v_bfe_u32 v36, v79, 16, 1
	v_add3_u32 v36, v79, v36, s10
	global_store_short_d16_hi v50, v36, s[2:3] offset:2560
	v_bfe_u32 v36, v126, 16, 1
	v_add3_u32 v36, v126, v36, s10
	global_store_short_d16_hi v50, v36, s[2:3] offset:2688
	v_bfe_u32 v36, v68, 16, 1
	v_add3_u32 v36, v68, v36, s10
	global_store_short_d16_hi v50, v36, s[2:3] offset:2816
	v_bfe_u32 v36, v160, 16, 1
	v_add3_u32 v36, v160, v36, s10
	global_store_short_d16_hi v50, v36, s[2:3] offset:2944
	v_bfe_u32 v36, v70, 16, 1
	v_add3_u32 v36, v70, v36, s10
	global_store_short_d16_hi v50, v36, s[2:3] offset:3072
	v_bfe_u32 v36, v64, 16, 1
	v_add3_u32 v36, v64, v36, s10
	global_store_short_d16_hi v50, v36, s[2:3] offset:3200
	v_bfe_u32 v36, v66, 16, 1
	v_add3_u32 v36, v66, v36, s10
	global_store_short_d16_hi v50, v36, s[2:3] offset:3328
	v_bfe_u32 v36, v62, 16, 1
	v_add3_u32 v36, v62, v36, s10
	global_store_short_d16_hi v50, v36, s[2:3] offset:3456
	v_bfe_u32 v36, v73, 16, 1
	v_add3_u32 v36, v73, v36, s10
	global_store_short_d16_hi v50, v36, s[2:3] offset:3584
	v_bfe_u32 v36, v122, 16, 1
	v_add3_u32 v36, v122, v36, s10
	global_store_short_d16_hi v50, v36, s[2:3] offset:3712
	v_bfe_u32 v36, v124, 16, 1
	v_add3_u32 v36, v124, v36, s10
	global_store_short_d16_hi v50, v36, s[2:3] offset:3840
	v_bfe_u32 v36, v96, 16, 1
	v_add3_u32 v36, v96, v36, s10
	v_lshl_add_u64 v[34:35], s[2:3], 0, v[50:51]
	global_store_short_d16_hi v50, v36, s[2:3] offset:3968
	s_movk_i32 s2, 0x1000
	v_bfe_u32 v36, v2, 16, 1
	v_add_co_u32_e32 v34, vcc, s2, v34
	v_add3_u32 v36, v2, v36, s10
	s_nop 0
	v_addc_co_u32_e32 v35, vcc, 0, v35, vcc
	global_store_short_d16_hi v[34:35], v36, off
	v_bfe_u32 v36, v3, 16, 1
	v_add3_u32 v36, v3, v36, s10
	global_store_short_d16_hi v[34:35], v36, off offset:128
	v_bfe_u32 v36, v4, 16, 1
	v_add3_u32 v36, v4, v36, s10
	global_store_short_d16_hi v[34:35], v36, off offset:256
	v_bfe_u32 v36, v5, 16, 1
	v_add3_u32 v36, v5, v36, s10
	global_store_short_d16_hi v[34:35], v36, off offset:384
	v_bfe_u32 v36, v6, 16, 1
	v_add3_u32 v36, v6, v36, s10
	global_store_short_d16_hi v[34:35], v36, off offset:512
	v_bfe_u32 v36, v7, 16, 1
	v_add3_u32 v36, v7, v36, s10
	global_store_short_d16_hi v[34:35], v36, off offset:640
	v_bfe_u32 v36, v8, 16, 1
	v_add3_u32 v36, v8, v36, s10
	global_store_short_d16_hi v[34:35], v36, off offset:768
	v_bfe_u32 v36, v9, 16, 1
	v_add3_u32 v36, v9, v36, s10
	global_store_short_d16_hi v[34:35], v36, off offset:896
	v_bfe_u32 v36, v10, 16, 1
	v_add3_u32 v36, v10, v36, s10
	global_store_short_d16_hi v[34:35], v36, off offset:1024
	v_bfe_u32 v36, v11, 16, 1
	v_add3_u32 v36, v11, v36, s10
	global_store_short_d16_hi v[34:35], v36, off offset:1152
	v_bfe_u32 v36, v12, 16, 1
	v_add3_u32 v36, v12, v36, s10
	global_store_short_d16_hi v[34:35], v36, off offset:1280
	v_bfe_u32 v36, v13, 16, 1
	v_add3_u32 v36, v13, v36, s10
	global_store_short_d16_hi v[34:35], v36, off offset:1408
	v_bfe_u32 v36, v14, 16, 1
	v_add3_u32 v36, v14, v36, s10
	global_store_short_d16_hi v[34:35], v36, off offset:1536
	v_bfe_u32 v36, v15, 16, 1
	v_add3_u32 v36, v15, v36, s10
	global_store_short_d16_hi v[34:35], v36, off offset:1664
	v_bfe_u32 v36, v16, 16, 1
	v_add3_u32 v36, v16, v36, s10
	global_store_short_d16_hi v[34:35], v36, off offset:1792
	v_bfe_u32 v36, v17, 16, 1
	v_add3_u32 v36, v17, v36, s10
	global_store_short_d16_hi v[34:35], v36, off offset:1920
	v_bfe_u32 v36, v18, 16, 1
	v_add3_u32 v36, v18, v36, s10
	global_store_short_d16_hi v[34:35], v36, off offset:2048
	v_bfe_u32 v36, v19, 16, 1
	v_add3_u32 v36, v19, v36, s10
	global_store_short_d16_hi v[34:35], v36, off offset:2176
	v_bfe_u32 v36, v20, 16, 1
	v_add3_u32 v36, v20, v36, s10
	global_store_short_d16_hi v[34:35], v36, off offset:2304
	v_bfe_u32 v36, v21, 16, 1
	v_add3_u32 v36, v21, v36, s10
	global_store_short_d16_hi v[34:35], v36, off offset:2432
	v_bfe_u32 v36, v22, 16, 1
	v_add3_u32 v36, v22, v36, s10
	global_store_short_d16_hi v[34:35], v36, off offset:2560
	v_bfe_u32 v36, v23, 16, 1
	v_add3_u32 v36, v23, v36, s10
	global_store_short_d16_hi v[34:35], v36, off offset:2688
	v_bfe_u32 v36, v24, 16, 1
	v_add3_u32 v36, v24, v36, s10
	global_store_short_d16_hi v[34:35], v36, off offset:2816
	v_bfe_u32 v36, v25, 16, 1
	v_add3_u32 v36, v25, v36, s10
	global_store_short_d16_hi v[34:35], v36, off offset:2944
	v_bfe_u32 v36, v26, 16, 1
	v_add3_u32 v36, v26, v36, s10
	global_store_short_d16_hi v[34:35], v36, off offset:3072
	v_bfe_u32 v36, v27, 16, 1
	v_add3_u32 v36, v27, v36, s10
	global_store_short_d16_hi v[34:35], v36, off offset:3200
	v_bfe_u32 v36, v28, 16, 1
	v_add3_u32 v36, v28, v36, s10
	global_store_short_d16_hi v[34:35], v36, off offset:3328
	v_bfe_u32 v36, v29, 16, 1
	v_add3_u32 v36, v29, v36, s10
	global_store_short_d16_hi v[34:35], v36, off offset:3456
	v_bfe_u32 v36, v30, 16, 1
	v_add3_u32 v36, v30, v36, s10
	global_store_short_d16_hi v[34:35], v36, off offset:3584
	v_bfe_u32 v36, v31, 16, 1
	v_add3_u32 v36, v31, v36, s10
	global_store_short_d16_hi v[34:35], v36, off offset:3712
	v_bfe_u32 v36, v32, 16, 1
	v_add3_u32 v36, v32, v36, s10
	global_store_short_d16_hi v[34:35], v36, off offset:3840
	v_bfe_u32 v36, v33, 16, 1
	v_add3_u32 v36, v33, v36, s10
	global_store_short_d16_hi v[34:35], v36, off offset:3968
	v_mov_b32_e32 v123, v73
	v_mov_b32_e32 v63, v66
	v_mov_b32_e32 v65, v70
	v_mov_b32_e32 v161, v68
	v_mov_b32_e32 v127, v79
	v_mov_b32_e32 v121, v76
	v_mov_b32_e32 v61, v92
	v_mov_b32_e32 v139, v142
	v_mov_b32_e32 v137, v141
	v_mov_b32_e32 v151, v172
	v_mov_b32_e32 v149, v170
	v_mov_b32_e32 v159, v168
	v_mov_b32_e32 v155, v167
	v_mov_b32_e32 v153, v164
	v_mov_b32_e32 v157, v163
	s_mov_b64 s[2:3], 0
	s_branch .LBB0_1066
